# GEMM MFMA phases: snake ordering inside each 8-MFMA group (every consecutive pair shares one operand fragment)
# speedup vs baseline: 1.0049x; 1.0049x over previous
; #define PG8_STAGE(bufoff, gbase, voff) do { _Pragma("unroll") for (int _i = 0; _i < 2; ++_i) \
;         __builtin_amdgcn_global_load_lds((const unsigned*)((const char*)(gbase) + (voff)[_i]), (LAS unsigned*)(lds + (bufoff) + ldsw + _i * 8192), 16, 0, 0); } while (0)
; #define PG8_LDA(dst, b, h) do { _Pragma("unroll") for (int m = 0; m < 4; ++m) _Pragma("unroll") for (int k = 0; k < 2; ++k) dst[m][k] = *(const LAS bf16x8*)(lds + PG8_SA(b, h) + aoff + m * 2048 + k * 1024); } while (0)
; #define PG8_LDB(dst, b, h) do { _Pragma("unroll") for (int n = 0; n < 2; ++n) _Pragma("unroll") for (int k = 0; k < 2; ++k) dst[n][k] = *(const LAS bf16x8*)(lds + PG8_SB(b, h) + boff + n * 2048 + k * 1024); } while (0)
; #define PG8_MMA(ai, bj, At, Bt) do { __builtin_amdgcn_s_setprio(1); _Pragma("unroll") for (int m = 0; m < 4; ++m) _Pragma("unroll") for (int n = 0; n < 2; ++n) _Pragma("unroll") for (int k = 0; k < 2; ++k) \
;         acc[ai][bj][m][n] = __builtin_amdgcn_mfma_f32_16x16x32_bf16(Bt[n][k], At[m][k], acc[ai][bj][m][n], 0, 0, 0); __builtin_amdgcn_s_setprio(0); } while (0)
; #define PG8_WAIT_V(n) asm volatile("s_waitcnt vmcnt(" #n ")" ::: "memory")
; #define PG8_WAIT_L(n) asm volatile("s_waitcnt lgkmcnt(" #n ")" ::: "memory")
; template <class Epi>
; __device__ __forceinline__ void gemm_phase(LAS unsigned char* lds, const Gemm g, const StaticOrder& S, const Epi& E) {
;     ...
;     for (;;) {
;         const bool has_next = S.next(ui + 1, nxt);
;         const char* nA = has_next ? (const char*)g.A + (size_t)nxt.pm * tA : cA; const char* nB = has_next ? (const char*)g.Bt + (size_t)nxt.pn * tB : cB;
;         for (int t = 0; t < nt; t += 2) {
;             const bool last = (t == nt - 2);
;             const char* a1 = cA + (size_t)(t + 1) * kstep;
;             const char* a2 = last ? nA : cA + (size_t)(t + 2) * kstep; const char* b2 = last ? nB : cB + (size_t)(t + 2) * kstep;
;             const char* a3 = a2 + kstep; const char* b3 = b2 + kstep;
;             PG8_LDB(B0, 0, 0); PG8_LDB(B1, 0, 1); PG8_SCHED; PG8_LDA(At, 0, 0); PG8_STAGE(PG8_SA(1, 1), a1 + hA, voffA);
;             PG8_WAIT_V(8); PG8_WAIT_L(0); PG8_BAR; PG8_MMA(0, 0, At, B0); PG8_MMA(0, 1, At, B1); PG8_BAR; PG8_SCHED;
;             PG8_LDA(At, 0, 1); PG8_STAGE(PG8_SB(0, 0), b2, voffB); PG8_STAGE(PG8_SB(0, 1), b2 + hB, voffB); PG8_STAGE(PG8_SA(0, 0), a2, voffA);
.LBB0_132:
	s_add_u32 s34, s8, 0xfffc0080
	s_addc_u32 s35, s9, -1
	s_add_i32 s42, 0, 0x10000
	s_cmp_eq_u32 s41, 12
	s_cselect_b32 s37, s7, s35
	s_cselect_b32 s36, s27, s34
	v_add_u32_e32 v153, s42, v139
	s_cselect_b32 s35, s25, s40
	s_cselect_b32 s34, s38, s39
	s_add_i32 s44, 0, 0x14000
	ds_read_b128 v[166:169], v153
	ds_read_b128 v[170:173], v153 offset:1024
	ds_read_b128 v[174:177], v153 offset:2048
	ds_read_b128 v[182:185], v153 offset:3072
	v_add_u32_e32 v153, s44, v139
	ds_read_b128 v[186:189], v153
	ds_read_b128 v[190:193], v153 offset:1024
	ds_read_b128 v[194:197], v153 offset:2048
	ds_read_b128 v[198:201], v153 offset:3072
	v_lshl_add_u64 v[178:179], s[8:9], 0, v[162:163]
	s_add_i32 m0, s19, 0xc000
	ds_read_b128 v[202:205], v149
	ds_read_b128 v[206:209], v149 offset:1024
	ds_read_b128 v[210:213], v149 offset:2048
	ds_read_b128 v[214:217], v149 offset:3072
	ds_read_b128 v[218:221], v149 offset:4096
	ds_read_b128 v[232:235], v149 offset:5120
	ds_read_b128 v[236:239], v149 offset:6144
	ds_read_b128 v[240:243], v149 offset:7168
	global_load_lds_dwordx4 v[178:179], off
	v_lshl_add_u64 v[178:179], s[8:9], 0, v[164:165]
	s_add_i32 m0, s19, 0xe000
	s_nop 0
	global_load_lds_dwordx4 v[178:179], off
	s_waitcnt vmcnt(8)
	s_waitcnt lgkmcnt(0)
	s_barrier
	s_setprio 1
	v_mfma_f32_16x16x32_bf16 v[126:129], v[166:169], v[202:205], v[126:129]
	v_mfma_f32_16x16x32_bf16 v[122:125], v[174:177], v[202:205], v[122:125]
	v_mfma_f32_16x16x32_bf16 v[106:109], v[174:177], v[210:213], v[106:109]
	v_mfma_f32_16x16x32_bf16 v[110:113], v[166:169], v[210:213], v[110:113]
	v_mfma_f32_16x16x32_bf16 v[94:97], v[166:169], v[218:221], v[94:97]
	v_mfma_f32_16x16x32_bf16 v[90:93], v[174:177], v[218:221], v[90:93]
	v_mfma_f32_16x16x32_bf16 v[74:77], v[174:177], v[236:239], v[74:77]
	v_mfma_f32_16x16x32_bf16 v[78:81], v[166:169], v[236:239], v[78:81]
	v_mfma_f32_16x16x32_bf16 v[126:129], v[170:173], v[206:209], v[126:129]
	v_mfma_f32_16x16x32_bf16 v[122:125], v[182:185], v[206:209], v[122:125]
	v_mfma_f32_16x16x32_bf16 v[106:109], v[182:185], v[214:217], v[106:109]
	v_mfma_f32_16x16x32_bf16 v[110:113], v[170:173], v[214:217], v[110:113]
	v_mfma_f32_16x16x32_bf16 v[94:97], v[170:173], v[232:235], v[94:97]
	v_mfma_f32_16x16x32_bf16 v[90:93], v[182:185], v[232:235], v[90:93]
	v_mfma_f32_16x16x32_bf16 v[74:77], v[182:185], v[240:243], v[74:77]
	v_mfma_f32_16x16x32_bf16 v[78:81], v[170:173], v[240:243], v[78:81]
	v_mfma_f32_16x16x32_bf16 v[118:121], v[186:189], v[202:205], v[118:121]
	v_mfma_f32_16x16x32_bf16 v[114:117], v[194:197], v[202:205], v[114:117]
	v_mfma_f32_16x16x32_bf16 v[98:101], v[194:197], v[210:213], v[98:101]
	v_mfma_f32_16x16x32_bf16 v[102:105], v[186:189], v[210:213], v[102:105]
	v_mfma_f32_16x16x32_bf16 v[86:89], v[186:189], v[218:221], v[86:89]
	v_mfma_f32_16x16x32_bf16 v[82:85], v[194:197], v[218:221], v[82:85]
	v_mfma_f32_16x16x32_bf16 v[66:69], v[194:197], v[236:239], v[66:69]
	v_mfma_f32_16x16x32_bf16 v[70:73], v[186:189], v[236:239], v[70:73]
	v_mfma_f32_16x16x32_bf16 v[118:121], v[190:193], v[206:209], v[118:121]
	v_mfma_f32_16x16x32_bf16 v[114:117], v[198:201], v[206:209], v[114:117]
	v_mfma_f32_16x16x32_bf16 v[98:101], v[198:201], v[214:217], v[98:101]
	v_mfma_f32_16x16x32_bf16 v[102:105], v[190:193], v[214:217], v[102:105]
	v_mfma_f32_16x16x32_bf16 v[86:89], v[190:193], v[232:235], v[86:89]
	v_mfma_f32_16x16x32_bf16 v[82:85], v[198:201], v[232:235], v[82:85]
	v_mfma_f32_16x16x32_bf16 v[66:69], v[198:201], v[240:243], v[66:69]
	v_mfma_f32_16x16x32_bf16 v[70:73], v[190:193], v[240:243], v[70:73]
	s_setprio 0
	s_barrier
	s_add_i32 s42, s42, s51
	v_lshl_add_u64 v[178:179], s[34:35], 0, v[132:133]
	s_mov_b32 m0, s42
	ds_read_b128 v[202:205], v149 offset:16384
	ds_read_b128 v[206:209], v149 offset:17408
	ds_read_b128 v[210:213], v149 offset:18432
	ds_read_b128 v[214:217], v149 offset:19456
	ds_read_b128 v[218:221], v149 offset:20480
	ds_read_b128 v[232:235], v149 offset:21504
	ds_read_b128 v[236:239], v149 offset:22528
	ds_read_b128 v[240:243], v149 offset:23552
	global_load_lds_dwordx4 v[178:179], off
	s_add_i32 m0, s42, 0x2000
	s_add_u32 s42, s34, 0x40000
	v_lshl_add_u64 v[244:245], s[34:35], 0, v[136:137]
	s_addc_u32 s43, s35, 0
	s_add_i32 s44, s44, s51
	global_load_lds_dwordx4 v[244:245], off
	v_lshl_add_u64 v[246:247], s[42:43], 0, v[132:133]
	s_mov_b32 m0, s44
	v_lshl_add_u64 v[248:249], s[36:37], 0, v[134:135]
	global_load_lds_dwordx4 v[246:247], off
	v_lshl_add_u64 v[246:247], s[42:43], 0, v[136:137]
	s_add_i32 m0, s44, 0x2000
	s_nop 0
	global_load_lds_dwordx4 v[246:247], off
	v_lshl_add_u64 v[246:247], s[36:37], 0, v[130:131]
	s_mov_b32 m0, s19
	s_nop 0
	global_load_lds_dwordx4 v[246:247], off
	s_mov_b32 m0, s56
	s_nop 0
	global_load_lds_dwordx4 v[248:249], off
	s_waitcnt vmcnt(8)
	s_waitcnt lgkmcnt(0)
	s_barrier
; #define PG8_STAGE(bufoff, gbase, voff) do { _Pragma("unroll") for (int _i = 0; _i < 2; ++_i) \
;         __builtin_amdgcn_global_load_lds((const unsigned*)((const char*)(gbase) + (voff)[_i]), (LAS unsigned*)(lds + (bufoff) + ldsw + _i * 8192), 16, 0, 0); } while (0)
; #define PG8_LDA(dst, b, h) do { _Pragma("unroll") for (int m = 0; m < 4; ++m) _Pragma("unroll") for (int k = 0; k < 2; ++k) dst[m][k] = *(const LAS bf16x8*)(lds + PG8_SA(b, h) + aoff + m * 2048 + k * 1024); } while (0)
; #define PG8_LDB(dst, b, h) do { _Pragma("unroll") for (int n = 0; n < 2; ++n) _Pragma("unroll") for (int k = 0; k < 2; ++k) dst[n][k] = *(const LAS bf16x8*)(lds + PG8_SB(b, h) + boff + n * 2048 + k * 1024); } while (0)
; #define PG8_MMA(ai, bj, At, Bt) do { __builtin_amdgcn_s_setprio(1); _Pragma("unroll") for (int m = 0; m < 4; ++m) _Pragma("unroll") for (int n = 0; n < 2; ++n) _Pragma("unroll") for (int k = 0; k < 2; ++k) \
;         acc[ai][bj][m][n] = __builtin_amdgcn_mfma_f32_16x16x32_bf16(Bt[n][k], At[m][k], acc[ai][bj][m][n], 0, 0, 0); __builtin_amdgcn_s_setprio(0); } while (0)
; #define PG8_WAIT_V(n) asm volatile("s_waitcnt vmcnt(" #n ")" ::: "memory")
; #define PG8_WAIT_L(n) asm volatile("s_waitcnt lgkmcnt(" #n ")" ::: "memory")
; #define PG8_BAR __builtin_amdgcn_s_barrier()
; #define PG8_SCHED __builtin_amdgcn_sched_barrier(0)
; template <class Epi>
; __device__ __forceinline__ void gemm_phase(LAS unsigned char* lds, const Gemm g, const StaticOrder& S, const Epi& E) {
;     ...
;             PG8_WAIT_V(8); PG8_WAIT_L(0); PG8_BAR; PG8_MMA(1, 0, At, B0); PG8_MMA(1, 1, At, B1); PG8_BAR; PG8_SCHED;
;             PG8_LDB(B0, 1, 0); PG8_LDB(B1, 1, 1); PG8_SCHED; PG8_LDA(At, 1, 0); PG8_STAGE(PG8_SA(0, 1), a2 + hA, voffA);
;             PG8_WAIT_V(8); PG8_WAIT_L(0); PG8_BAR; PG8_MMA(0, 0, At, B0); PG8_MMA(0, 1, At, B1); PG8_BAR; PG8_SCHED;
	s_setprio 1
	v_mfma_f32_16x16x32_bf16 v[62:65], v[166:169], v[202:205], v[62:65]
	v_mfma_f32_16x16x32_bf16 v[58:61], v[174:177], v[202:205], v[58:61]
	v_mfma_f32_16x16x32_bf16 v[42:45], v[174:177], v[210:213], v[42:45]
	v_mfma_f32_16x16x32_bf16 v[46:49], v[166:169], v[210:213], v[46:49]
	v_mfma_f32_16x16x32_bf16 v[30:33], v[166:169], v[218:221], v[30:33]
	v_mfma_f32_16x16x32_bf16 v[26:29], v[174:177], v[218:221], v[26:29]
	v_mfma_f32_16x16x32_bf16 v[10:13], v[174:177], v[236:239], v[10:13]
	v_mfma_f32_16x16x32_bf16 v[14:17], v[166:169], v[236:239], v[14:17]
	v_mfma_f32_16x16x32_bf16 v[62:65], v[170:173], v[206:209], v[62:65]
	v_mfma_f32_16x16x32_bf16 v[58:61], v[182:185], v[206:209], v[58:61]
	v_mfma_f32_16x16x32_bf16 v[42:45], v[182:185], v[214:217], v[42:45]
	v_mfma_f32_16x16x32_bf16 v[46:49], v[170:173], v[214:217], v[46:49]
	v_mfma_f32_16x16x32_bf16 v[30:33], v[170:173], v[232:235], v[30:33]
	v_mfma_f32_16x16x32_bf16 v[26:29], v[182:185], v[232:235], v[26:29]
	v_mfma_f32_16x16x32_bf16 v[10:13], v[182:185], v[240:243], v[10:13]
	v_mfma_f32_16x16x32_bf16 v[14:17], v[170:173], v[240:243], v[14:17]
	v_mfma_f32_16x16x32_bf16 v[54:57], v[186:189], v[202:205], v[54:57]
	v_mfma_f32_16x16x32_bf16 v[50:53], v[194:197], v[202:205], v[50:53]
	v_mfma_f32_16x16x32_bf16 v[34:37], v[194:197], v[210:213], v[34:37]
	v_mfma_f32_16x16x32_bf16 v[38:41], v[186:189], v[210:213], v[38:41]
	v_mfma_f32_16x16x32_bf16 v[22:25], v[186:189], v[218:221], v[22:25]
	v_mfma_f32_16x16x32_bf16 v[18:21], v[194:197], v[218:221], v[18:21]
	v_mfma_f32_16x16x32_bf16 v[2:5], v[194:197], v[236:239], v[2:5]
	v_mfma_f32_16x16x32_bf16 v[6:9], v[186:189], v[236:239], v[6:9]
	v_mfma_f32_16x16x32_bf16 v[54:57], v[190:193], v[206:209], v[54:57]
	v_mfma_f32_16x16x32_bf16 v[50:53], v[198:201], v[206:209], v[50:53]
	v_mfma_f32_16x16x32_bf16 v[34:37], v[198:201], v[214:217], v[34:37]
	v_mfma_f32_16x16x32_bf16 v[38:41], v[190:193], v[214:217], v[38:41]
	v_mfma_f32_16x16x32_bf16 v[22:25], v[190:193], v[232:235], v[22:25]
	v_mfma_f32_16x16x32_bf16 v[18:21], v[198:201], v[232:235], v[18:21]
	v_mfma_f32_16x16x32_bf16 v[2:5], v[198:201], v[240:243], v[2:5]
	v_mfma_f32_16x16x32_bf16 v[6:9], v[190:193], v[240:243], v[6:9]
	s_setprio 0
	s_barrier
	s_add_i32 s42, 0, 0x18000
	v_add_u32_e32 v153, s42, v139
	s_add_i32 s43, 0, 0x1c000
	ds_read_b128 v[166:169], v153
	ds_read_b128 v[170:173], v153 offset:1024
	ds_read_b128 v[174:177], v153 offset:2048
	ds_read_b128 v[182:185], v153 offset:3072
	v_add_u32_e32 v153, s43, v139
	ds_read_b128 v[186:189], v153
	ds_read_b128 v[190:193], v153 offset:1024
	ds_read_b128 v[194:197], v153 offset:2048
	ds_read_b128 v[198:201], v153 offset:3072
	s_add_u32 s36, s36, 0x40000
	s_addc_u32 s37, s37, 0
	s_mov_b32 m0, s57
	v_lshl_add_u64 v[250:251], s[36:37], 0, v[130:131]
	ds_read_b128 v[202:205], v149 offset:32768
	ds_read_b128 v[206:209], v149 offset:33792
	ds_read_b128 v[210:213], v149 offset:34816
	ds_read_b128 v[214:217], v149 offset:35840
	ds_read_b128 v[218:221], v149 offset:36864
	ds_read_b128 v[232:235], v149 offset:37888
	ds_read_b128 v[236:239], v149 offset:38912
	ds_read_b128 v[240:243], v149 offset:39936
	global_load_lds_dwordx4 v[250:251], off
	v_lshl_add_u64 v[250:251], s[36:37], 0, v[134:135]
	s_mov_b32 m0, s58
	s_nop 0
	global_load_lds_dwordx4 v[250:251], off
	s_waitcnt vmcnt(8)
	s_waitcnt lgkmcnt(0)
	s_barrier
	s_setprio 1
	v_mfma_f32_16x16x32_bf16 v[126:129], v[166:169], v[202:205], v[126:129]
	v_mfma_f32_16x16x32_bf16 v[122:125], v[174:177], v[202:205], v[122:125]
	v_mfma_f32_16x16x32_bf16 v[106:109], v[174:177], v[210:213], v[106:109]
	v_mfma_f32_16x16x32_bf16 v[110:113], v[166:169], v[210:213], v[110:113]
	v_mfma_f32_16x16x32_bf16 v[94:97], v[166:169], v[218:221], v[94:97]
	v_mfma_f32_16x16x32_bf16 v[90:93], v[174:177], v[218:221], v[90:93]
	v_mfma_f32_16x16x32_bf16 v[74:77], v[174:177], v[236:239], v[74:77]
	v_mfma_f32_16x16x32_bf16 v[78:81], v[166:169], v[236:239], v[78:81]
	v_mfma_f32_16x16x32_bf16 v[126:129], v[170:173], v[206:209], v[126:129]
	v_mfma_f32_16x16x32_bf16 v[122:125], v[182:185], v[206:209], v[122:125]
	v_mfma_f32_16x16x32_bf16 v[106:109], v[182:185], v[214:217], v[106:109]
	v_mfma_f32_16x16x32_bf16 v[110:113], v[170:173], v[214:217], v[110:113]
	v_mfma_f32_16x16x32_bf16 v[94:97], v[170:173], v[232:235], v[94:97]
	v_mfma_f32_16x16x32_bf16 v[90:93], v[182:185], v[232:235], v[90:93]
	v_mfma_f32_16x16x32_bf16 v[74:77], v[182:185], v[240:243], v[74:77]
	v_mfma_f32_16x16x32_bf16 v[78:81], v[170:173], v[240:243], v[78:81]
	v_mfma_f32_16x16x32_bf16 v[118:121], v[186:189], v[202:205], v[118:121]
	v_mfma_f32_16x16x32_bf16 v[114:117], v[194:197], v[202:205], v[114:117]
	v_mfma_f32_16x16x32_bf16 v[98:101], v[194:197], v[210:213], v[98:101]
	v_mfma_f32_16x16x32_bf16 v[102:105], v[186:189], v[210:213], v[102:105]
	v_mfma_f32_16x16x32_bf16 v[86:89], v[186:189], v[218:221], v[86:89]
	v_mfma_f32_16x16x32_bf16 v[82:85], v[194:197], v[218:221], v[82:85]
	v_mfma_f32_16x16x32_bf16 v[66:69], v[194:197], v[236:239], v[66:69]
	v_mfma_f32_16x16x32_bf16 v[70:73], v[186:189], v[236:239], v[70:73]
	v_mfma_f32_16x16x32_bf16 v[118:121], v[190:193], v[206:209], v[118:121]
	v_mfma_f32_16x16x32_bf16 v[114:117], v[198:201], v[206:209], v[114:117]
	v_mfma_f32_16x16x32_bf16 v[98:101], v[198:201], v[214:217], v[98:101]
	v_mfma_f32_16x16x32_bf16 v[102:105], v[190:193], v[214:217], v[102:105]
	v_mfma_f32_16x16x32_bf16 v[86:89], v[190:193], v[232:235], v[86:89]
	v_mfma_f32_16x16x32_bf16 v[82:85], v[198:201], v[232:235], v[82:85]
	v_mfma_f32_16x16x32_bf16 v[66:69], v[198:201], v[240:243], v[66:69]
	v_mfma_f32_16x16x32_bf16 v[70:73], v[190:193], v[240:243], v[70:73]
	s_setprio 0
	s_barrier
; #define PG8_STAGE(bufoff, gbase, voff) do { _Pragma("unroll") for (int _i = 0; _i < 2; ++_i) \
;         __builtin_amdgcn_global_load_lds((const unsigned*)((const char*)(gbase) + (voff)[_i]), (LAS unsigned*)(lds + (bufoff) + ldsw + _i * 8192), 16, 0, 0); } while (0)
; #define PG8_LDA(dst, b, h) do { _Pragma("unroll") for (int m = 0; m < 4; ++m) _Pragma("unroll") for (int k = 0; k < 2; ++k) dst[m][k] = *(const LAS bf16x8*)(lds + PG8_SA(b, h) + aoff + m * 2048 + k * 1024); } while (0)
; #define PG8_MMA(ai, bj, At, Bt) do { __builtin_amdgcn_s_setprio(1); _Pragma("unroll") for (int m = 0; m < 4; ++m) _Pragma("unroll") for (int n = 0; n < 2; ++n) _Pragma("unroll") for (int k = 0; k < 2; ++k) \
;         acc[ai][bj][m][n] = __builtin_amdgcn_mfma_f32_16x16x32_bf16(Bt[n][k], At[m][k], acc[ai][bj][m][n], 0, 0, 0); __builtin_amdgcn_s_setprio(0); } while (0)
; #define PG8_WAIT_V(n) asm volatile("s_waitcnt vmcnt(" #n ")" ::: "memory")
; #define PG8_WAIT_L(n) asm volatile("s_waitcnt lgkmcnt(" #n ")" ::: "memory")
; #define PG8_BAR __builtin_amdgcn_s_barrier()
; #define PG8_SCHED __builtin_amdgcn_sched_barrier(0)
; template <class Epi>
; __device__ __forceinline__ void gemm_phase(LAS unsigned char* lds, const Gemm g, const StaticOrder& S, const Epi& E) {
;     ...
;             PG8_LDA(At, 1, 1); PG8_STAGE(PG8_SB(1, 0), b3, voffB); PG8_STAGE(PG8_SB(1, 1), b3 + hB, voffB); PG8_STAGE(PG8_SA(1, 0), a3, voffA);
;             PG8_WAIT_V(8); PG8_WAIT_L(0); PG8_BAR; PG8_MMA(1, 0, At, B0); PG8_MMA(1, 1, At, B1); PG8_BAR; PG8_SCHED;
;         }
;         if (wr == 0) PG8_BAR;
	s_add_i32 s36, s42, s51
	v_lshl_add_u64 v[178:179], v[178:179], 0, s[88:89]
	s_mov_b32 m0, s36
	ds_read_b128 v[202:205], v149 offset:49152
	ds_read_b128 v[206:209], v149 offset:50176
	ds_read_b128 v[210:213], v149 offset:51200
	ds_read_b128 v[214:217], v149 offset:52224
	ds_read_b128 v[218:221], v149 offset:53248
	ds_read_b128 v[232:235], v149 offset:54272
	ds_read_b128 v[236:239], v149 offset:55296
	ds_read_b128 v[240:243], v149 offset:56320
	global_load_lds_dwordx4 v[178:179], off
	s_add_i32 m0, s36, 0x2000
	s_add_u32 s34, s34, 0x40080
	v_lshl_add_u64 v[178:179], v[244:245], 0, s[88:89]
	s_addc_u32 s35, s35, 0
	s_add_i32 s36, s43, s51
	global_load_lds_dwordx4 v[178:179], off
	v_lshl_add_u64 v[178:179], s[34:35], 0, v[132:133]
	s_mov_b32 m0, s36
	s_nop 0
	global_load_lds_dwordx4 v[178:179], off
	v_lshl_add_u64 v[178:179], s[34:35], 0, v[136:137]
	s_add_i32 m0, s36, 0x2000
	s_nop 0
	global_load_lds_dwordx4 v[178:179], off
	v_lshl_add_u64 v[178:179], v[246:247], 0, s[88:89]
	s_mov_b32 m0, s60
	s_nop 0
	global_load_lds_dwordx4 v[178:179], off
	v_lshl_add_u64 v[178:179], v[248:249], 0, s[88:89]
	s_mov_b32 m0, s61
	s_nop 0
	global_load_lds_dwordx4 v[178:179], off
	s_waitcnt vmcnt(8)
	s_waitcnt lgkmcnt(0)
	s_barrier
	s_setprio 1
	v_mfma_f32_16x16x32_bf16 v[62:65], v[166:169], v[202:205], v[62:65]
	v_mfma_f32_16x16x32_bf16 v[58:61], v[174:177], v[202:205], v[58:61]
	v_mfma_f32_16x16x32_bf16 v[42:45], v[174:177], v[210:213], v[42:45]
	v_mfma_f32_16x16x32_bf16 v[46:49], v[166:169], v[210:213], v[46:49]
	v_mfma_f32_16x16x32_bf16 v[30:33], v[166:169], v[218:221], v[30:33]
	v_mfma_f32_16x16x32_bf16 v[26:29], v[174:177], v[218:221], v[26:29]
	v_mfma_f32_16x16x32_bf16 v[10:13], v[174:177], v[236:239], v[10:13]
	v_mfma_f32_16x16x32_bf16 v[14:17], v[166:169], v[236:239], v[14:17]
	v_mfma_f32_16x16x32_bf16 v[62:65], v[170:173], v[206:209], v[62:65]
	v_mfma_f32_16x16x32_bf16 v[58:61], v[182:185], v[206:209], v[58:61]
	v_mfma_f32_16x16x32_bf16 v[42:45], v[182:185], v[214:217], v[42:45]
	v_mfma_f32_16x16x32_bf16 v[46:49], v[170:173], v[214:217], v[46:49]
	v_mfma_f32_16x16x32_bf16 v[30:33], v[170:173], v[232:235], v[30:33]
	v_mfma_f32_16x16x32_bf16 v[26:29], v[182:185], v[232:235], v[26:29]
	v_mfma_f32_16x16x32_bf16 v[10:13], v[182:185], v[240:243], v[10:13]
	v_mfma_f32_16x16x32_bf16 v[14:17], v[170:173], v[240:243], v[14:17]
	v_mfma_f32_16x16x32_bf16 v[54:57], v[186:189], v[202:205], v[54:57]
	v_mfma_f32_16x16x32_bf16 v[50:53], v[194:197], v[202:205], v[50:53]
	v_mfma_f32_16x16x32_bf16 v[34:37], v[194:197], v[210:213], v[34:37]
	v_mfma_f32_16x16x32_bf16 v[38:41], v[186:189], v[210:213], v[38:41]
	v_mfma_f32_16x16x32_bf16 v[22:25], v[186:189], v[218:221], v[22:25]
	v_mfma_f32_16x16x32_bf16 v[18:21], v[194:197], v[218:221], v[18:21]
	v_mfma_f32_16x16x32_bf16 v[2:5], v[194:197], v[236:239], v[2:5]
	v_mfma_f32_16x16x32_bf16 v[6:9], v[186:189], v[236:239], v[6:9]
	v_mfma_f32_16x16x32_bf16 v[54:57], v[190:193], v[206:209], v[54:57]
	v_mfma_f32_16x16x32_bf16 v[50:53], v[198:201], v[206:209], v[50:53]
	v_mfma_f32_16x16x32_bf16 v[34:37], v[198:201], v[214:217], v[34:37]
	v_mfma_f32_16x16x32_bf16 v[38:41], v[190:193], v[214:217], v[38:41]
	v_mfma_f32_16x16x32_bf16 v[22:25], v[190:193], v[232:235], v[22:25]
	v_mfma_f32_16x16x32_bf16 v[18:21], v[198:201], v[232:235], v[18:21]
	v_mfma_f32_16x16x32_bf16 v[2:5], v[198:201], v[240:243], v[2:5]
	v_mfma_f32_16x16x32_bf16 v[6:9], v[190:193], v[240:243], v[6:9]
	s_setprio 0
	s_barrier
	s_add_i32 s41, s41, 2
	s_add_u32 s8, s8, 0x100
	s_addc_u32 s9, s9, 0
	s_add_u32 s39, s39, 0x100
	s_addc_u32 s40, s40, 0
	s_cmp_gt_u32 s41, 13
	s_cbranch_scc0 .LBB0_132
	s_and_b64 vcc, exec, s[16:17]
	s_cbranch_vccz .LBB0_135
	s_barrier

; #define PG8_STAGE(bufoff, gbase, voff) do { _Pragma("unroll") for (int _i = 0; _i < 2; ++_i) \
;         __builtin_amdgcn_global_load_lds((const unsigned*)((const char*)(gbase) + (voff)[_i]), (LAS unsigned*)(lds + (bufoff) + ldsw + _i * 8192), 16, 0, 0); } while (0)
; #define PG8_LDA(dst, b, h) do { _Pragma("unroll") for (int m = 0; m < 4; ++m) _Pragma("unroll") for (int k = 0; k < 2; ++k) dst[m][k] = *(const LAS bf16x8*)(lds + PG8_SA(b, h) + aoff + m * 2048 + k * 1024); } while (0)
; #define PG8_LDB(dst, b, h) do { _Pragma("unroll") for (int n = 0; n < 2; ++n) _Pragma("unroll") for (int k = 0; k < 2; ++k) dst[n][k] = *(const LAS bf16x8*)(lds + PG8_SB(b, h) + boff + n * 2048 + k * 1024); } while (0)
; #define PG8_MMA(ai, bj, At, Bt) do { __builtin_amdgcn_s_setprio(1); _Pragma("unroll") for (int m = 0; m < 4; ++m) _Pragma("unroll") for (int n = 0; n < 2; ++n) _Pragma("unroll") for (int k = 0; k < 2; ++k) \
;         acc[ai][bj][m][n] = __builtin_amdgcn_mfma_f32_16x16x32_bf16(Bt[n][k], At[m][k], acc[ai][bj][m][n], 0, 0, 0); __builtin_amdgcn_s_setprio(0); } while (0)
; #define PG8_WAIT_V(n) asm volatile("s_waitcnt vmcnt(" #n ")" ::: "memory")
; #define PG8_WAIT_L(n) asm volatile("s_waitcnt lgkmcnt(" #n ")" ::: "memory")
; #define PG8_BAR __builtin_amdgcn_s_barrier()
; #define PG8_SCHED __builtin_amdgcn_sched_barrier(0)
; template <class Epi>
; __device__ __forceinline__ void gemm_phase(LAS unsigned char* lds, const Gemm g, const StaticOrder& S, const Epi& E) {
;     ...
;             PG8_LDB(B0, 0, 0); PG8_LDB(B1, 0, 1); PG8_SCHED; PG8_LDA(At, 0, 0); PG8_STAGE(PG8_SA(1, 1), a1 + hA, voffA);
;             PG8_WAIT_V(8); PG8_WAIT_L(0); PG8_BAR; PG8_MMA(0, 0, At, B0); PG8_MMA(0, 1, At, B1); PG8_BAR; PG8_SCHED;
;             PG8_LDA(At, 0, 1); PG8_STAGE(PG8_SB(0, 0), b2, voffB); PG8_STAGE(PG8_SB(0, 1), b2 + hB, voffB); PG8_STAGE(PG8_SA(0, 0), a2, voffA);
.LBB0_518:
	s_add_u32 s30, s28, 0xfffc0080
	s_addc_u32 s31, s29, -1
	s_add_i32 s71, 0, 0x10000
	s_cmp_eq_u32 s70, 28
	s_cselect_b32 s35, s21, s31
	s_cselect_b32 s34, s27, s30
	v_add_u32_e32 v154, s71, v156
	s_cselect_b32 s31, s19, s67
	s_cselect_b32 s30, s65, s66
	s_add_i32 s73, 0, 0x14000
	ds_read_b128 v[98:101], v154
	ds_read_b128 v[102:105], v154 offset:1024
	ds_read_b128 v[158:161], v154 offset:2048
	ds_read_b128 v[162:165], v154 offset:3072
	v_add_u32_e32 v154, s73, v156
	ds_read_b128 v[166:169], v154
	ds_read_b128 v[170:173], v154 offset:1024
	ds_read_b128 v[174:177], v154 offset:2048
	ds_read_b128 v[182:185], v154 offset:3072
	v_lshl_add_u64 v[154:155], s[28:29], 0, v[150:151]
	s_add_i32 m0, s54, 0xc000
	ds_read_b128 v[186:189], v157
	ds_read_b128 v[190:193], v157 offset:1024
	ds_read_b128 v[194:197], v157 offset:2048
	ds_read_b128 v[198:201], v157 offset:3072
	ds_read_b128 v[202:205], v157 offset:4096
	ds_read_b128 v[206:209], v157 offset:5120
	ds_read_b128 v[210:213], v157 offset:6144
	ds_read_b128 v[214:217], v157 offset:7168
	global_load_lds_dwordx4 v[154:155], off
	v_lshl_add_u64 v[154:155], s[28:29], 0, v[152:153]
	s_add_i32 m0, s54, 0xe000
	s_nop 0
	global_load_lds_dwordx4 v[154:155], off
	s_waitcnt vmcnt(8)
	s_waitcnt lgkmcnt(0)
	s_barrier
	s_setprio 1
	v_mfma_f32_16x16x32_bf16 v[134:137], v[98:101], v[186:189], v[134:137]
	v_mfma_f32_16x16x32_bf16 v[130:133], v[158:161], v[186:189], v[130:133]
	v_mfma_f32_16x16x32_bf16 v[122:125], v[158:161], v[194:197], v[122:125]
	v_mfma_f32_16x16x32_bf16 v[126:129], v[98:101], v[194:197], v[126:129]
	v_mfma_f32_16x16x32_bf16 v[118:121], v[98:101], v[202:205], v[118:121]
	v_mfma_f32_16x16x32_bf16 v[114:117], v[158:161], v[202:205], v[114:117]
	v_mfma_f32_16x16x32_bf16 v[106:109], v[158:161], v[210:213], v[106:109]
	v_mfma_f32_16x16x32_bf16 v[110:113], v[98:101], v[210:213], v[110:113]
	v_mfma_f32_16x16x32_bf16 v[134:137], v[102:105], v[190:193], v[134:137]
	v_mfma_f32_16x16x32_bf16 v[130:133], v[162:165], v[190:193], v[130:133]
	v_mfma_f32_16x16x32_bf16 v[122:125], v[162:165], v[198:201], v[122:125]
	v_mfma_f32_16x16x32_bf16 v[126:129], v[102:105], v[198:201], v[126:129]
	v_mfma_f32_16x16x32_bf16 v[118:121], v[102:105], v[206:209], v[118:121]
	v_mfma_f32_16x16x32_bf16 v[114:117], v[162:165], v[206:209], v[114:117]
	v_mfma_f32_16x16x32_bf16 v[106:109], v[162:165], v[214:217], v[106:109]
	v_mfma_f32_16x16x32_bf16 v[110:113], v[102:105], v[214:217], v[110:113]
	v_mfma_f32_16x16x32_bf16 v[62:65], v[166:169], v[186:189], v[62:65]
	v_mfma_f32_16x16x32_bf16 v[58:61], v[174:177], v[186:189], v[58:61]
	v_mfma_f32_16x16x32_bf16 v[50:53], v[174:177], v[194:197], v[50:53]
	v_mfma_f32_16x16x32_bf16 v[54:57], v[166:169], v[194:197], v[54:57]
	v_mfma_f32_16x16x32_bf16 v[46:49], v[166:169], v[202:205], v[46:49]
	v_mfma_f32_16x16x32_bf16 v[42:45], v[174:177], v[202:205], v[42:45]
	v_mfma_f32_16x16x32_bf16 v[34:37], v[174:177], v[210:213], v[34:37]
	v_mfma_f32_16x16x32_bf16 v[38:41], v[166:169], v[210:213], v[38:41]
	v_mfma_f32_16x16x32_bf16 v[62:65], v[170:173], v[190:193], v[62:65]
	v_mfma_f32_16x16x32_bf16 v[58:61], v[182:185], v[190:193], v[58:61]
	v_mfma_f32_16x16x32_bf16 v[50:53], v[182:185], v[198:201], v[50:53]
	v_mfma_f32_16x16x32_bf16 v[54:57], v[170:173], v[198:201], v[54:57]
	v_mfma_f32_16x16x32_bf16 v[46:49], v[170:173], v[206:209], v[46:49]
	v_mfma_f32_16x16x32_bf16 v[42:45], v[182:185], v[206:209], v[42:45]
	v_mfma_f32_16x16x32_bf16 v[34:37], v[182:185], v[214:217], v[34:37]
	v_mfma_f32_16x16x32_bf16 v[38:41], v[170:173], v[214:217], v[38:41]
	s_setprio 0
	s_barrier
	s_add_i32 s71, s71, s53
	v_lshl_add_u64 v[154:155], s[30:31], 0, v[140:141]
	s_mov_b32 m0, s71
	ds_read_b128 v[186:189], v157 offset:16384
	ds_read_b128 v[190:193], v157 offset:17408
	ds_read_b128 v[194:197], v157 offset:18432
	ds_read_b128 v[198:201], v157 offset:19456
	ds_read_b128 v[202:205], v157 offset:20480
	ds_read_b128 v[206:209], v157 offset:21504
	ds_read_b128 v[210:213], v157 offset:22528
	ds_read_b128 v[214:217], v157 offset:23552
	global_load_lds_dwordx4 v[154:155], off
	s_add_i32 m0, s71, 0x2000
	s_add_u32 s74, s30, 0x80000
	v_lshl_add_u64 v[178:179], s[30:31], 0, v[144:145]
	s_addc_u32 s75, s31, 0
	s_add_i32 s71, s73, s53
	global_load_lds_dwordx4 v[178:179], off
	v_lshl_add_u64 v[218:219], s[74:75], 0, v[140:141]
	s_mov_b32 m0, s71
	v_lshl_add_u64 v[220:221], s[34:35], 0, v[142:143]
	global_load_lds_dwordx4 v[218:219], off
	v_lshl_add_u64 v[218:219], s[74:75], 0, v[144:145]
	s_add_i32 m0, s71, 0x2000
	s_nop 0
	global_load_lds_dwordx4 v[218:219], off
	v_lshl_add_u64 v[218:219], s[34:35], 0, v[138:139]
	s_mov_b32 m0, s54
	s_nop 0
	global_load_lds_dwordx4 v[218:219], off
	s_mov_b32 m0, s55
	s_nop 0
	global_load_lds_dwordx4 v[220:221], off
	s_waitcnt vmcnt(8)
	s_waitcnt lgkmcnt(0)
	s_barrier
; #define PG8_STAGE(bufoff, gbase, voff) do { _Pragma("unroll") for (int _i = 0; _i < 2; ++_i) \
;         __builtin_amdgcn_global_load_lds((const unsigned*)((const char*)(gbase) + (voff)[_i]), (LAS unsigned*)(lds + (bufoff) + ldsw + _i * 8192), 16, 0, 0); } while (0)
; #define PG8_LDA(dst, b, h) do { _Pragma("unroll") for (int m = 0; m < 4; ++m) _Pragma("unroll") for (int k = 0; k < 2; ++k) dst[m][k] = *(const LAS bf16x8*)(lds + PG8_SA(b, h) + aoff + m * 2048 + k * 1024); } while (0)
; #define PG8_LDB(dst, b, h) do { _Pragma("unroll") for (int n = 0; n < 2; ++n) _Pragma("unroll") for (int k = 0; k < 2; ++k) dst[n][k] = *(const LAS bf16x8*)(lds + PG8_SB(b, h) + boff + n * 2048 + k * 1024); } while (0)
; #define PG8_MMA(ai, bj, At, Bt) do { __builtin_amdgcn_s_setprio(1); _Pragma("unroll") for (int m = 0; m < 4; ++m) _Pragma("unroll") for (int n = 0; n < 2; ++n) _Pragma("unroll") for (int k = 0; k < 2; ++k) \
;         acc[ai][bj][m][n] = __builtin_amdgcn_mfma_f32_16x16x32_bf16(Bt[n][k], At[m][k], acc[ai][bj][m][n], 0, 0, 0); __builtin_amdgcn_s_setprio(0); } while (0)
; #define PG8_WAIT_V(n) asm volatile("s_waitcnt vmcnt(" #n ")" ::: "memory")
; #define PG8_WAIT_L(n) asm volatile("s_waitcnt lgkmcnt(" #n ")" ::: "memory")
; #define PG8_BAR __builtin_amdgcn_s_barrier()
; #define PG8_SCHED __builtin_amdgcn_sched_barrier(0)
; template <class Epi>
; __device__ __forceinline__ void gemm_phase(LAS unsigned char* lds, const Gemm g, const StaticOrder& S, const Epi& E) {
;     ...
;             PG8_WAIT_V(8); PG8_WAIT_L(0); PG8_BAR; PG8_MMA(1, 0, At, B0); PG8_MMA(1, 1, At, B1); PG8_BAR; PG8_SCHED;
;             PG8_LDB(B0, 1, 0); PG8_LDB(B1, 1, 1); PG8_SCHED; PG8_LDA(At, 1, 0); PG8_STAGE(PG8_SA(0, 1), a2 + hA, voffA);
;             PG8_WAIT_V(8); PG8_WAIT_L(0); PG8_BAR; PG8_MMA(0, 0, At, B0); PG8_MMA(0, 1, At, B1); PG8_BAR; PG8_SCHED;
	s_setprio 1
	v_mfma_f32_16x16x32_bf16 v[94:97], v[98:101], v[186:189], v[94:97]
	v_mfma_f32_16x16x32_bf16 v[90:93], v[158:161], v[186:189], v[90:93]
	v_mfma_f32_16x16x32_bf16 v[82:85], v[158:161], v[194:197], v[82:85]
	v_mfma_f32_16x16x32_bf16 v[86:89], v[98:101], v[194:197], v[86:89]
	v_mfma_f32_16x16x32_bf16 v[78:81], v[98:101], v[202:205], v[78:81]
	v_mfma_f32_16x16x32_bf16 v[74:77], v[158:161], v[202:205], v[74:77]
	v_mfma_f32_16x16x32_bf16 v[66:69], v[158:161], v[210:213], v[66:69]
	v_mfma_f32_16x16x32_bf16 v[70:73], v[98:101], v[210:213], v[70:73]
	v_mfma_f32_16x16x32_bf16 v[94:97], v[102:105], v[190:193], v[94:97]
	v_mfma_f32_16x16x32_bf16 v[90:93], v[162:165], v[190:193], v[90:93]
	v_mfma_f32_16x16x32_bf16 v[82:85], v[162:165], v[198:201], v[82:85]
	v_mfma_f32_16x16x32_bf16 v[86:89], v[102:105], v[198:201], v[86:89]
	v_mfma_f32_16x16x32_bf16 v[78:81], v[102:105], v[206:209], v[78:81]
	v_mfma_f32_16x16x32_bf16 v[74:77], v[162:165], v[206:209], v[74:77]
	v_mfma_f32_16x16x32_bf16 v[66:69], v[162:165], v[214:217], v[66:69]
	v_mfma_f32_16x16x32_bf16 v[70:73], v[102:105], v[214:217], v[70:73]
	v_mfma_f32_16x16x32_bf16 v[30:33], v[166:169], v[186:189], v[30:33]
	v_mfma_f32_16x16x32_bf16 v[26:29], v[174:177], v[186:189], v[26:29]
	v_mfma_f32_16x16x32_bf16 v[18:21], v[174:177], v[194:197], v[18:21]
	v_mfma_f32_16x16x32_bf16 v[22:25], v[166:169], v[194:197], v[22:25]
	v_mfma_f32_16x16x32_bf16 v[14:17], v[166:169], v[202:205], v[14:17]
	v_mfma_f32_16x16x32_bf16 v[10:13], v[174:177], v[202:205], v[10:13]
	v_mfma_f32_16x16x32_bf16 v[2:5], v[174:177], v[210:213], v[2:5]
	v_mfma_f32_16x16x32_bf16 v[6:9], v[166:169], v[210:213], v[6:9]
	v_mfma_f32_16x16x32_bf16 v[30:33], v[170:173], v[190:193], v[30:33]
	v_mfma_f32_16x16x32_bf16 v[26:29], v[182:185], v[190:193], v[26:29]
	v_mfma_f32_16x16x32_bf16 v[18:21], v[182:185], v[198:201], v[18:21]
	v_mfma_f32_16x16x32_bf16 v[22:25], v[170:173], v[198:201], v[22:25]
	v_mfma_f32_16x16x32_bf16 v[14:17], v[170:173], v[206:209], v[14:17]
	v_mfma_f32_16x16x32_bf16 v[10:13], v[182:185], v[206:209], v[10:13]
	v_mfma_f32_16x16x32_bf16 v[2:5], v[182:185], v[214:217], v[2:5]
	v_mfma_f32_16x16x32_bf16 v[6:9], v[170:173], v[214:217], v[6:9]
	s_setprio 0
	s_barrier
	s_add_i32 s71, 0, 0x18000
	s_add_i32 s73, 0, 0x1c000
	v_add_u32_e32 v162, s71, v156
	v_add_u32_e32 v180, s73, v156
	ds_read_b128 v[98:101], v162
	ds_read_b128 v[102:105], v162 offset:1024
	ds_read_b128 v[158:161], v162 offset:2048
	ds_read_b128 v[162:165], v162 offset:3072
	ds_read_b128 v[166:169], v180
	ds_read_b128 v[170:173], v180 offset:1024
	ds_read_b128 v[174:177], v180 offset:2048
	ds_read_b128 v[182:185], v180 offset:3072
	s_add_u32 s34, s34, 0x40000
	s_addc_u32 s35, s35, 0
	s_mov_b32 m0, s56
	v_lshl_add_u64 v[232:233], s[34:35], 0, v[138:139]
	ds_read_b128 v[186:189], v157 offset:32768
	ds_read_b128 v[190:193], v157 offset:33792
	ds_read_b128 v[194:197], v157 offset:34816
	ds_read_b128 v[198:201], v157 offset:35840
	ds_read_b128 v[202:205], v157 offset:36864
	ds_read_b128 v[206:209], v157 offset:37888
	ds_read_b128 v[210:213], v157 offset:38912
	ds_read_b128 v[214:217], v157 offset:39936
	global_load_lds_dwordx4 v[232:233], off
	v_lshl_add_u64 v[232:233], s[34:35], 0, v[142:143]
	s_mov_b32 m0, s57
	s_nop 0
	global_load_lds_dwordx4 v[232:233], off
	s_waitcnt vmcnt(8)
	s_waitcnt lgkmcnt(0)
	s_barrier
	s_setprio 1
	v_mfma_f32_16x16x32_bf16 v[134:137], v[98:101], v[186:189], v[134:137]
	v_mfma_f32_16x16x32_bf16 v[130:133], v[158:161], v[186:189], v[130:133]
	v_mfma_f32_16x16x32_bf16 v[122:125], v[158:161], v[194:197], v[122:125]
	v_mfma_f32_16x16x32_bf16 v[126:129], v[98:101], v[194:197], v[126:129]
	v_mfma_f32_16x16x32_bf16 v[118:121], v[98:101], v[202:205], v[118:121]
	v_mfma_f32_16x16x32_bf16 v[114:117], v[158:161], v[202:205], v[114:117]
	v_mfma_f32_16x16x32_bf16 v[106:109], v[158:161], v[210:213], v[106:109]
	v_mfma_f32_16x16x32_bf16 v[110:113], v[98:101], v[210:213], v[110:113]
	v_mfma_f32_16x16x32_bf16 v[134:137], v[102:105], v[190:193], v[134:137]
	v_mfma_f32_16x16x32_bf16 v[130:133], v[162:165], v[190:193], v[130:133]
	v_mfma_f32_16x16x32_bf16 v[122:125], v[162:165], v[198:201], v[122:125]
	v_mfma_f32_16x16x32_bf16 v[126:129], v[102:105], v[198:201], v[126:129]
	v_mfma_f32_16x16x32_bf16 v[118:121], v[102:105], v[206:209], v[118:121]
	v_mfma_f32_16x16x32_bf16 v[114:117], v[162:165], v[206:209], v[114:117]
	v_mfma_f32_16x16x32_bf16 v[106:109], v[162:165], v[214:217], v[106:109]
	v_mfma_f32_16x16x32_bf16 v[110:113], v[102:105], v[214:217], v[110:113]
	v_mfma_f32_16x16x32_bf16 v[62:65], v[166:169], v[186:189], v[62:65]
	v_mfma_f32_16x16x32_bf16 v[58:61], v[174:177], v[186:189], v[58:61]
	v_mfma_f32_16x16x32_bf16 v[50:53], v[174:177], v[194:197], v[50:53]
	v_mfma_f32_16x16x32_bf16 v[54:57], v[166:169], v[194:197], v[54:57]
	v_mfma_f32_16x16x32_bf16 v[46:49], v[166:169], v[202:205], v[46:49]
	v_mfma_f32_16x16x32_bf16 v[42:45], v[174:177], v[202:205], v[42:45]
	v_mfma_f32_16x16x32_bf16 v[34:37], v[174:177], v[210:213], v[34:37]
	v_mfma_f32_16x16x32_bf16 v[38:41], v[166:169], v[210:213], v[38:41]
	v_mfma_f32_16x16x32_bf16 v[62:65], v[170:173], v[190:193], v[62:65]
	v_mfma_f32_16x16x32_bf16 v[58:61], v[182:185], v[190:193], v[58:61]
	v_mfma_f32_16x16x32_bf16 v[50:53], v[182:185], v[198:201], v[50:53]
	v_mfma_f32_16x16x32_bf16 v[54:57], v[170:173], v[198:201], v[54:57]
	v_mfma_f32_16x16x32_bf16 v[46:49], v[170:173], v[206:209], v[46:49]
	v_mfma_f32_16x16x32_bf16 v[42:45], v[182:185], v[206:209], v[42:45]
	v_mfma_f32_16x16x32_bf16 v[34:37], v[182:185], v[214:217], v[34:37]
	v_mfma_f32_16x16x32_bf16 v[38:41], v[170:173], v[214:217], v[38:41]
	s_setprio 0
	s_barrier
; #define PG8_STAGE(bufoff, gbase, voff) do { _Pragma("unroll") for (int _i = 0; _i < 2; ++_i) \
;         __builtin_amdgcn_global_load_lds((const unsigned*)((const char*)(gbase) + (voff)[_i]), (LAS unsigned*)(lds + (bufoff) + ldsw + _i * 8192), 16, 0, 0); } while (0)
; #define PG8_LDA(dst, b, h) do { _Pragma("unroll") for (int m = 0; m < 4; ++m) _Pragma("unroll") for (int k = 0; k < 2; ++k) dst[m][k] = *(const LAS bf16x8*)(lds + PG8_SA(b, h) + aoff + m * 2048 + k * 1024); } while (0)
; #define PG8_MMA(ai, bj, At, Bt) do { __builtin_amdgcn_s_setprio(1); _Pragma("unroll") for (int m = 0; m < 4; ++m) _Pragma("unroll") for (int n = 0; n < 2; ++n) _Pragma("unroll") for (int k = 0; k < 2; ++k) \
;         acc[ai][bj][m][n] = __builtin_amdgcn_mfma_f32_16x16x32_bf16(Bt[n][k], At[m][k], acc[ai][bj][m][n], 0, 0, 0); __builtin_amdgcn_s_setprio(0); } while (0)
; #define PG8_WAIT_V(n) asm volatile("s_waitcnt vmcnt(" #n ")" ::: "memory")
; #define PG8_WAIT_L(n) asm volatile("s_waitcnt lgkmcnt(" #n ")" ::: "memory")
; #define PG8_BAR __builtin_amdgcn_s_barrier()
; #define PG8_SCHED __builtin_amdgcn_sched_barrier(0)
; template <class Epi>
; __device__ __forceinline__ void gemm_phase(LAS unsigned char* lds, const Gemm g, const StaticOrder& S, const Epi& E) {
;     ...
;             PG8_LDA(At, 1, 1); PG8_STAGE(PG8_SB(1, 0), b3, voffB); PG8_STAGE(PG8_SB(1, 1), b3 + hB, voffB); PG8_STAGE(PG8_SA(1, 0), a3, voffA);
;             PG8_WAIT_V(8); PG8_WAIT_L(0); PG8_BAR; PG8_MMA(1, 0, At, B0); PG8_MMA(1, 1, At, B1); PG8_BAR; PG8_SCHED;
;         }
;         if (wr == 0) PG8_BAR;
	s_add_i32 s34, s71, s53
	v_lshl_add_u64 v[154:155], v[154:155], 0, s[88:89]
	s_mov_b32 m0, s34
	ds_read_b128 v[186:189], v157 offset:49152
	ds_read_b128 v[190:193], v157 offset:50176
	ds_read_b128 v[194:197], v157 offset:51200
	ds_read_b128 v[198:201], v157 offset:52224
	ds_read_b128 v[202:205], v157 offset:53248
	ds_read_b128 v[206:209], v157 offset:54272
	ds_read_b128 v[210:213], v157 offset:55296
	ds_read_b128 v[214:217], v157 offset:56320
	global_load_lds_dwordx4 v[154:155], off
	s_add_i32 m0, s34, 0x2000
	s_add_u32 s30, s30, 0x80080
	v_lshl_add_u64 v[154:155], v[178:179], 0, s[88:89]
	s_addc_u32 s31, s31, 0
	s_add_i32 s34, s73, s53
	global_load_lds_dwordx4 v[154:155], off
	v_lshl_add_u64 v[154:155], s[30:31], 0, v[140:141]
	s_mov_b32 m0, s34
	s_nop 0
	global_load_lds_dwordx4 v[154:155], off
	v_lshl_add_u64 v[154:155], s[30:31], 0, v[144:145]
	s_add_i32 m0, s34, 0x2000
	s_nop 0
	global_load_lds_dwordx4 v[154:155], off
	v_lshl_add_u64 v[154:155], v[218:219], 0, s[88:89]
	s_mov_b32 m0, s59
	s_nop 0
	global_load_lds_dwordx4 v[154:155], off
	v_lshl_add_u64 v[154:155], v[220:221], 0, s[88:89]
	s_mov_b32 m0, s60
	s_nop 0
	global_load_lds_dwordx4 v[154:155], off
	s_waitcnt vmcnt(8)
	s_waitcnt lgkmcnt(0)
	s_barrier
	s_setprio 1
	v_mfma_f32_16x16x32_bf16 v[94:97], v[98:101], v[186:189], v[94:97]
	v_mfma_f32_16x16x32_bf16 v[90:93], v[158:161], v[186:189], v[90:93]
	v_mfma_f32_16x16x32_bf16 v[82:85], v[158:161], v[194:197], v[82:85]
	v_mfma_f32_16x16x32_bf16 v[86:89], v[98:101], v[194:197], v[86:89]
	v_mfma_f32_16x16x32_bf16 v[78:81], v[98:101], v[202:205], v[78:81]
	v_mfma_f32_16x16x32_bf16 v[74:77], v[158:161], v[202:205], v[74:77]
	v_mfma_f32_16x16x32_bf16 v[66:69], v[158:161], v[210:213], v[66:69]
	v_mfma_f32_16x16x32_bf16 v[70:73], v[98:101], v[210:213], v[70:73]
	v_mfma_f32_16x16x32_bf16 v[94:97], v[102:105], v[190:193], v[94:97]
	v_mfma_f32_16x16x32_bf16 v[90:93], v[162:165], v[190:193], v[90:93]
	v_mfma_f32_16x16x32_bf16 v[82:85], v[162:165], v[198:201], v[82:85]
	v_mfma_f32_16x16x32_bf16 v[86:89], v[102:105], v[198:201], v[86:89]
	v_mfma_f32_16x16x32_bf16 v[78:81], v[102:105], v[206:209], v[78:81]
	v_mfma_f32_16x16x32_bf16 v[74:77], v[162:165], v[206:209], v[74:77]
	v_mfma_f32_16x16x32_bf16 v[66:69], v[162:165], v[214:217], v[66:69]
	v_mfma_f32_16x16x32_bf16 v[70:73], v[102:105], v[214:217], v[70:73]
	v_mfma_f32_16x16x32_bf16 v[30:33], v[166:169], v[186:189], v[30:33]
	v_mfma_f32_16x16x32_bf16 v[26:29], v[174:177], v[186:189], v[26:29]
	v_mfma_f32_16x16x32_bf16 v[18:21], v[174:177], v[194:197], v[18:21]
	v_mfma_f32_16x16x32_bf16 v[22:25], v[166:169], v[194:197], v[22:25]
	v_mfma_f32_16x16x32_bf16 v[14:17], v[166:169], v[202:205], v[14:17]
	v_mfma_f32_16x16x32_bf16 v[10:13], v[174:177], v[202:205], v[10:13]
	v_mfma_f32_16x16x32_bf16 v[2:5], v[174:177], v[210:213], v[2:5]
	v_mfma_f32_16x16x32_bf16 v[6:9], v[166:169], v[210:213], v[6:9]
	v_mfma_f32_16x16x32_bf16 v[30:33], v[170:173], v[190:193], v[30:33]
	v_mfma_f32_16x16x32_bf16 v[26:29], v[182:185], v[190:193], v[26:29]
	v_mfma_f32_16x16x32_bf16 v[18:21], v[182:185], v[198:201], v[18:21]
	v_mfma_f32_16x16x32_bf16 v[22:25], v[170:173], v[198:201], v[22:25]
	v_mfma_f32_16x16x32_bf16 v[14:17], v[170:173], v[206:209], v[14:17]
	v_mfma_f32_16x16x32_bf16 v[10:13], v[182:185], v[206:209], v[10:13]
	v_mfma_f32_16x16x32_bf16 v[2:5], v[182:185], v[214:217], v[2:5]
	v_mfma_f32_16x16x32_bf16 v[6:9], v[170:173], v[214:217], v[6:9]
	s_setprio 0
	s_barrier
	s_add_i32 s70, s70, 2
	s_add_u32 s28, s28, 0x100
	s_addc_u32 s29, s29, 0
	s_add_u32 s66, s66, 0x100
	s_addc_u32 s67, s67, 0
	s_cmp_gt_u32 s70, 29
	s_cbranch_scc0 .LBB0_518
	s_and_b64 vcc, exec, s[16:17]
	s_cbranch_vccz .LBB0_521
	s_barrier

; #define PG8_STAGE(bufoff, gbase, voff) do { _Pragma("unroll") for (int _i = 0; _i < 2; ++_i) \
;         __builtin_amdgcn_global_load_lds((const unsigned*)((const char*)(gbase) + (voff)[_i]), (LAS unsigned*)(lds + (bufoff) + ldsw + _i * 8192), 16, 0, 0); } while (0)
; #define PG8_LDA(dst, b, h) do { _Pragma("unroll") for (int m = 0; m < 4; ++m) _Pragma("unroll") for (int k = 0; k < 2; ++k) dst[m][k] = *(const LAS bf16x8*)(lds + PG8_SA(b, h) + aoff + m * 2048 + k * 1024); } while (0)
; #define PG8_LDB(dst, b, h) do { _Pragma("unroll") for (int n = 0; n < 2; ++n) _Pragma("unroll") for (int k = 0; k < 2; ++k) dst[n][k] = *(const LAS bf16x8*)(lds + PG8_SB(b, h) + boff + n * 2048 + k * 1024); } while (0)
; #define PG8_MMA(ai, bj, At, Bt) do { __builtin_amdgcn_s_setprio(1); _Pragma("unroll") for (int m = 0; m < 4; ++m) _Pragma("unroll") for (int n = 0; n < 2; ++n) _Pragma("unroll") for (int k = 0; k < 2; ++k) \
;         acc[ai][bj][m][n] = __builtin_amdgcn_mfma_f32_16x16x32_bf16(Bt[n][k], At[m][k], acc[ai][bj][m][n], 0, 0, 0); __builtin_amdgcn_s_setprio(0); } while (0)
; #define PG8_WAIT_V(n) asm volatile("s_waitcnt vmcnt(" #n ")" ::: "memory")
; #define PG8_WAIT_L(n) asm volatile("s_waitcnt lgkmcnt(" #n ")" ::: "memory")
; #define PG8_BAR __builtin_amdgcn_s_barrier()
; #define PG8_SCHED __builtin_amdgcn_sched_barrier(0)
; template <class Epi>
; __device__ __forceinline__ void gemm_phase(LAS unsigned char* lds, const Gemm g, const StaticOrder& S, const Epi& E) {
;     ...
;             PG8_LDB(B0, 0, 0); PG8_LDB(B1, 0, 1); PG8_SCHED; PG8_LDA(At, 0, 0); PG8_STAGE(PG8_SA(1, 1), a1 + hA, voffA);
;             PG8_WAIT_V(8); PG8_WAIT_L(0); PG8_BAR; PG8_MMA(0, 0, At, B0); PG8_MMA(0, 1, At, B1); PG8_BAR; PG8_SCHED;
;             PG8_LDA(At, 0, 1); PG8_STAGE(PG8_SB(0, 0), b2, voffB); PG8_STAGE(PG8_SB(0, 1), b2 + hB, voffB); PG8_STAGE(PG8_SA(0, 0), a2, voffA);
.LBB0_1398:
	s_add_u32 s10, s8, 0xfffc0080
	s_addc_u32 s11, s9, -1
	s_add_i32 s35, 0, 0x10000
	s_cmp_eq_u32 s31, 12
	s_cselect_b32 s41, s37, s11
	s_cselect_b32 s40, s36, s10
	s_cselect_b32 s11, s39, s29
	s_cselect_b32 s10, s38, s27
	s_add_i32 s64, 0, 0x14000
	v_add_u32_e32 v158, s35, v180
	v_add_u32_e32 v174, s64, v180
	ds_read_b128 v[146:149], v158
	ds_read_b128 v[150:153], v158 offset:1024
	ds_read_b128 v[154:157], v158 offset:2048
	ds_read_b128 v[158:161], v158 offset:3072
	ds_read_b128 v[162:165], v174
	ds_read_b128 v[166:169], v174 offset:1024
	ds_read_b128 v[170:173], v174 offset:2048
	ds_read_b128 v[174:177], v174 offset:3072
	v_lshl_add_u64 v[178:179], s[8:9], 0, v[142:143]
	s_add_i32 m0, s51, 0xc000
	ds_read_b128 v[182:185], v211
	ds_read_b128 v[186:189], v211 offset:1024
	ds_read_b128 v[190:193], v211 offset:2048
	ds_read_b128 v[194:197], v211 offset:3072
	ds_read_b128 v[198:201], v211 offset:4096
	ds_read_b128 v[202:205], v211 offset:5120
	ds_read_b128 v[216:219], v211 offset:6144
	ds_read_b128 v[232:235], v211 offset:7168
	global_load_lds_dwordx4 v[178:179], off
	v_lshl_add_u64 v[178:179], s[8:9], 0, v[144:145]
	s_add_i32 m0, s51, 0xe000
	s_nop 0
	global_load_lds_dwordx4 v[178:179], off
	s_waitcnt vmcnt(8)
	s_waitcnt lgkmcnt(0)
	s_barrier
	s_setprio 1
	v_mfma_f32_16x16x32_bf16 v[126:129], v[146:149], v[182:185], v[126:129]
	v_mfma_f32_16x16x32_bf16 v[122:125], v[154:157], v[182:185], v[122:125]
	v_mfma_f32_16x16x32_bf16 v[106:109], v[154:157], v[190:193], v[106:109]
	v_mfma_f32_16x16x32_bf16 v[110:113], v[146:149], v[190:193], v[110:113]
	v_mfma_f32_16x16x32_bf16 v[94:97], v[146:149], v[198:201], v[94:97]
	v_mfma_f32_16x16x32_bf16 v[90:93], v[154:157], v[198:201], v[90:93]
	v_mfma_f32_16x16x32_bf16 v[74:77], v[154:157], v[216:219], v[74:77]
	v_mfma_f32_16x16x32_bf16 v[78:81], v[146:149], v[216:219], v[78:81]
	v_mfma_f32_16x16x32_bf16 v[126:129], v[150:153], v[186:189], v[126:129]
	v_mfma_f32_16x16x32_bf16 v[122:125], v[158:161], v[186:189], v[122:125]
	v_mfma_f32_16x16x32_bf16 v[106:109], v[158:161], v[194:197], v[106:109]
	v_mfma_f32_16x16x32_bf16 v[110:113], v[150:153], v[194:197], v[110:113]
	v_mfma_f32_16x16x32_bf16 v[94:97], v[150:153], v[202:205], v[94:97]
	v_mfma_f32_16x16x32_bf16 v[90:93], v[158:161], v[202:205], v[90:93]
	v_mfma_f32_16x16x32_bf16 v[74:77], v[158:161], v[232:235], v[74:77]
	v_mfma_f32_16x16x32_bf16 v[78:81], v[150:153], v[232:235], v[78:81]
	v_mfma_f32_16x16x32_bf16 v[118:121], v[162:165], v[182:185], v[118:121]
	v_mfma_f32_16x16x32_bf16 v[114:117], v[170:173], v[182:185], v[114:117]
	v_mfma_f32_16x16x32_bf16 v[98:101], v[170:173], v[190:193], v[98:101]
	v_mfma_f32_16x16x32_bf16 v[102:105], v[162:165], v[190:193], v[102:105]
	v_mfma_f32_16x16x32_bf16 v[86:89], v[162:165], v[198:201], v[86:89]
	v_mfma_f32_16x16x32_bf16 v[82:85], v[170:173], v[198:201], v[82:85]
	v_mfma_f32_16x16x32_bf16 v[66:69], v[170:173], v[216:219], v[66:69]
	v_mfma_f32_16x16x32_bf16 v[70:73], v[162:165], v[216:219], v[70:73]
	v_mfma_f32_16x16x32_bf16 v[118:121], v[166:169], v[186:189], v[118:121]
	v_mfma_f32_16x16x32_bf16 v[114:117], v[174:177], v[186:189], v[114:117]
	v_mfma_f32_16x16x32_bf16 v[98:101], v[174:177], v[194:197], v[98:101]
	v_mfma_f32_16x16x32_bf16 v[102:105], v[166:169], v[194:197], v[102:105]
	v_mfma_f32_16x16x32_bf16 v[86:89], v[166:169], v[202:205], v[86:89]
	v_mfma_f32_16x16x32_bf16 v[82:85], v[174:177], v[202:205], v[82:85]
	v_mfma_f32_16x16x32_bf16 v[66:69], v[174:177], v[232:235], v[66:69]
	v_mfma_f32_16x16x32_bf16 v[70:73], v[166:169], v[232:235], v[70:73]
	s_setprio 0
	s_barrier
	s_add_i32 s35, s35, s50
	v_lshl_add_u64 v[178:179], s[10:11], 0, v[132:133]
	s_mov_b32 m0, s35
	ds_read_b128 v[182:185], v211 offset:16384
	ds_read_b128 v[186:189], v211 offset:17408
	ds_read_b128 v[190:193], v211 offset:18432
	ds_read_b128 v[194:197], v211 offset:19456
	ds_read_b128 v[198:201], v211 offset:20480
	ds_read_b128 v[202:205], v211 offset:21504
	ds_read_b128 v[216:219], v211 offset:22528
	ds_read_b128 v[232:235], v211 offset:23552
	global_load_lds_dwordx4 v[178:179], off
	s_add_i32 m0, s35, 0x2000
	s_add_u32 s42, s10, 0x40000
	v_lshl_add_u64 v[206:207], s[10:11], 0, v[136:137]
	s_addc_u32 s43, s11, 0
	s_add_i32 s35, s64, s50
	global_load_lds_dwordx4 v[206:207], off
	v_lshl_add_u64 v[220:221], s[42:43], 0, v[132:133]
	s_mov_b32 m0, s35
	v_lshl_add_u64 v[236:237], s[40:41], 0, v[134:135]
	global_load_lds_dwordx4 v[220:221], off
	v_lshl_add_u64 v[220:221], s[42:43], 0, v[136:137]
	s_add_i32 m0, s35, 0x2000
	s_nop 0
	global_load_lds_dwordx4 v[220:221], off
	v_lshl_add_u64 v[220:221], s[40:41], 0, v[130:131]
	s_mov_b32 m0, s51
	s_nop 0
	global_load_lds_dwordx4 v[220:221], off
	s_mov_b32 m0, s52
	s_nop 0
	global_load_lds_dwordx4 v[236:237], off
	s_waitcnt vmcnt(8)
	s_waitcnt lgkmcnt(0)
	s_barrier
; #define PG8_STAGE(bufoff, gbase, voff) do { _Pragma("unroll") for (int _i = 0; _i < 2; ++_i) \
;         __builtin_amdgcn_global_load_lds((const unsigned*)((const char*)(gbase) + (voff)[_i]), (LAS unsigned*)(lds + (bufoff) + ldsw + _i * 8192), 16, 0, 0); } while (0)
; #define PG8_LDA(dst, b, h) do { _Pragma("unroll") for (int m = 0; m < 4; ++m) _Pragma("unroll") for (int k = 0; k < 2; ++k) dst[m][k] = *(const LAS bf16x8*)(lds + PG8_SA(b, h) + aoff + m * 2048 + k * 1024); } while (0)
; #define PG8_LDB(dst, b, h) do { _Pragma("unroll") for (int n = 0; n < 2; ++n) _Pragma("unroll") for (int k = 0; k < 2; ++k) dst[n][k] = *(const LAS bf16x8*)(lds + PG8_SB(b, h) + boff + n * 2048 + k * 1024); } while (0)
; #define PG8_MMA(ai, bj, At, Bt) do { __builtin_amdgcn_s_setprio(1); _Pragma("unroll") for (int m = 0; m < 4; ++m) _Pragma("unroll") for (int n = 0; n < 2; ++n) _Pragma("unroll") for (int k = 0; k < 2; ++k) \
;         acc[ai][bj][m][n] = __builtin_amdgcn_mfma_f32_16x16x32_bf16(Bt[n][k], At[m][k], acc[ai][bj][m][n], 0, 0, 0); __builtin_amdgcn_s_setprio(0); } while (0)
; #define PG8_WAIT_V(n) asm volatile("s_waitcnt vmcnt(" #n ")" ::: "memory")
; #define PG8_WAIT_L(n) asm volatile("s_waitcnt lgkmcnt(" #n ")" ::: "memory")
; #define PG8_BAR __builtin_amdgcn_s_barrier()
; #define PG8_SCHED __builtin_amdgcn_sched_barrier(0)
; template <class Epi>
; __device__ __forceinline__ void gemm_phase(LAS unsigned char* lds, const Gemm g, const StaticOrder& S, const Epi& E) {
;     ...
;             PG8_WAIT_V(8); PG8_WAIT_L(0); PG8_BAR; PG8_MMA(1, 0, At, B0); PG8_MMA(1, 1, At, B1); PG8_BAR; PG8_SCHED;
;             PG8_LDB(B0, 1, 0); PG8_LDB(B1, 1, 1); PG8_SCHED; PG8_LDA(At, 1, 0); PG8_STAGE(PG8_SA(0, 1), a2 + hA, voffA);
;             PG8_WAIT_V(8); PG8_WAIT_L(0); PG8_BAR; PG8_MMA(0, 0, At, B0); PG8_MMA(0, 1, At, B1); PG8_BAR; PG8_SCHED;
	s_setprio 1
	v_mfma_f32_16x16x32_bf16 v[62:65], v[146:149], v[182:185], v[62:65]
	v_mfma_f32_16x16x32_bf16 v[58:61], v[154:157], v[182:185], v[58:61]
	v_mfma_f32_16x16x32_bf16 v[42:45], v[154:157], v[190:193], v[42:45]
	v_mfma_f32_16x16x32_bf16 v[46:49], v[146:149], v[190:193], v[46:49]
	v_mfma_f32_16x16x32_bf16 v[30:33], v[146:149], v[198:201], v[30:33]
	v_mfma_f32_16x16x32_bf16 v[26:29], v[154:157], v[198:201], v[26:29]
	v_mfma_f32_16x16x32_bf16 v[10:13], v[154:157], v[216:219], v[10:13]
	v_mfma_f32_16x16x32_bf16 v[14:17], v[146:149], v[216:219], v[14:17]
	v_mfma_f32_16x16x32_bf16 v[62:65], v[150:153], v[186:189], v[62:65]
	v_mfma_f32_16x16x32_bf16 v[58:61], v[158:161], v[186:189], v[58:61]
	v_mfma_f32_16x16x32_bf16 v[42:45], v[158:161], v[194:197], v[42:45]
	v_mfma_f32_16x16x32_bf16 v[46:49], v[150:153], v[194:197], v[46:49]
	v_mfma_f32_16x16x32_bf16 v[30:33], v[150:153], v[202:205], v[30:33]
	v_mfma_f32_16x16x32_bf16 v[26:29], v[158:161], v[202:205], v[26:29]
	v_mfma_f32_16x16x32_bf16 v[10:13], v[158:161], v[232:235], v[10:13]
	v_mfma_f32_16x16x32_bf16 v[14:17], v[150:153], v[232:235], v[14:17]
	v_mfma_f32_16x16x32_bf16 v[54:57], v[162:165], v[182:185], v[54:57]
	v_mfma_f32_16x16x32_bf16 v[50:53], v[170:173], v[182:185], v[50:53]
	v_mfma_f32_16x16x32_bf16 v[34:37], v[170:173], v[190:193], v[34:37]
	v_mfma_f32_16x16x32_bf16 v[38:41], v[162:165], v[190:193], v[38:41]
	v_mfma_f32_16x16x32_bf16 v[22:25], v[162:165], v[198:201], v[22:25]
	v_mfma_f32_16x16x32_bf16 v[18:21], v[170:173], v[198:201], v[18:21]
	v_mfma_f32_16x16x32_bf16 v[2:5], v[170:173], v[216:219], v[2:5]
	v_mfma_f32_16x16x32_bf16 v[6:9], v[162:165], v[216:219], v[6:9]
	v_mfma_f32_16x16x32_bf16 v[54:57], v[166:169], v[186:189], v[54:57]
	v_mfma_f32_16x16x32_bf16 v[50:53], v[174:177], v[186:189], v[50:53]
	v_mfma_f32_16x16x32_bf16 v[34:37], v[174:177], v[194:197], v[34:37]
	v_mfma_f32_16x16x32_bf16 v[38:41], v[166:169], v[194:197], v[38:41]
	v_mfma_f32_16x16x32_bf16 v[22:25], v[166:169], v[202:205], v[22:25]
	v_mfma_f32_16x16x32_bf16 v[18:21], v[174:177], v[202:205], v[18:21]
	v_mfma_f32_16x16x32_bf16 v[2:5], v[174:177], v[232:235], v[2:5]
	v_mfma_f32_16x16x32_bf16 v[6:9], v[166:169], v[232:235], v[6:9]
	s_setprio 0
	s_barrier
	s_add_i32 s35, 0, 0x18000
	s_add_i32 s42, 0, 0x1c000
	v_add_u32_e32 v158, s35, v180
	v_add_u32_e32 v174, s42, v180
	ds_read_b128 v[146:149], v158
	ds_read_b128 v[150:153], v158 offset:1024
	ds_read_b128 v[154:157], v158 offset:2048
	ds_read_b128 v[158:161], v158 offset:3072
	ds_read_b128 v[162:165], v174
	ds_read_b128 v[166:169], v174 offset:1024
	ds_read_b128 v[170:173], v174 offset:2048
	ds_read_b128 v[174:177], v174 offset:3072
	s_add_u32 s40, s40, 0x40000
	s_addc_u32 s41, s41, 0
	s_mov_b32 m0, s53
	v_lshl_add_u64 v[238:239], s[40:41], 0, v[130:131]
	ds_read_b128 v[182:185], v211 offset:32768
	ds_read_b128 v[186:189], v211 offset:33792
	ds_read_b128 v[190:193], v211 offset:34816
	ds_read_b128 v[194:197], v211 offset:35840
	ds_read_b128 v[198:201], v211 offset:36864
	ds_read_b128 v[202:205], v211 offset:37888
	ds_read_b128 v[216:219], v211 offset:38912
	ds_read_b128 v[232:235], v211 offset:39936
	global_load_lds_dwordx4 v[238:239], off
	v_lshl_add_u64 v[238:239], s[40:41], 0, v[134:135]
	s_mov_b32 m0, s54
	s_nop 0
	global_load_lds_dwordx4 v[238:239], off
	s_waitcnt vmcnt(8)
	s_waitcnt lgkmcnt(0)
	s_barrier
	s_setprio 1
	v_mfma_f32_16x16x32_bf16 v[126:129], v[146:149], v[182:185], v[126:129]
	v_mfma_f32_16x16x32_bf16 v[122:125], v[154:157], v[182:185], v[122:125]
	v_mfma_f32_16x16x32_bf16 v[106:109], v[154:157], v[190:193], v[106:109]
	v_mfma_f32_16x16x32_bf16 v[110:113], v[146:149], v[190:193], v[110:113]
	v_mfma_f32_16x16x32_bf16 v[94:97], v[146:149], v[198:201], v[94:97]
	v_mfma_f32_16x16x32_bf16 v[90:93], v[154:157], v[198:201], v[90:93]
	v_mfma_f32_16x16x32_bf16 v[74:77], v[154:157], v[216:219], v[74:77]
	v_mfma_f32_16x16x32_bf16 v[78:81], v[146:149], v[216:219], v[78:81]
	v_mfma_f32_16x16x32_bf16 v[126:129], v[150:153], v[186:189], v[126:129]
	v_mfma_f32_16x16x32_bf16 v[122:125], v[158:161], v[186:189], v[122:125]
	v_mfma_f32_16x16x32_bf16 v[106:109], v[158:161], v[194:197], v[106:109]
	v_mfma_f32_16x16x32_bf16 v[110:113], v[150:153], v[194:197], v[110:113]
	v_mfma_f32_16x16x32_bf16 v[94:97], v[150:153], v[202:205], v[94:97]
	v_mfma_f32_16x16x32_bf16 v[90:93], v[158:161], v[202:205], v[90:93]
	v_mfma_f32_16x16x32_bf16 v[74:77], v[158:161], v[232:235], v[74:77]
	v_mfma_f32_16x16x32_bf16 v[78:81], v[150:153], v[232:235], v[78:81]
	v_mfma_f32_16x16x32_bf16 v[118:121], v[162:165], v[182:185], v[118:121]
	v_mfma_f32_16x16x32_bf16 v[114:117], v[170:173], v[182:185], v[114:117]
	v_mfma_f32_16x16x32_bf16 v[98:101], v[170:173], v[190:193], v[98:101]
	v_mfma_f32_16x16x32_bf16 v[102:105], v[162:165], v[190:193], v[102:105]
	v_mfma_f32_16x16x32_bf16 v[86:89], v[162:165], v[198:201], v[86:89]
	v_mfma_f32_16x16x32_bf16 v[82:85], v[170:173], v[198:201], v[82:85]
	v_mfma_f32_16x16x32_bf16 v[66:69], v[170:173], v[216:219], v[66:69]
	v_mfma_f32_16x16x32_bf16 v[70:73], v[162:165], v[216:219], v[70:73]
	v_mfma_f32_16x16x32_bf16 v[118:121], v[166:169], v[186:189], v[118:121]
	v_mfma_f32_16x16x32_bf16 v[114:117], v[174:177], v[186:189], v[114:117]
	v_mfma_f32_16x16x32_bf16 v[98:101], v[174:177], v[194:197], v[98:101]
	v_mfma_f32_16x16x32_bf16 v[102:105], v[166:169], v[194:197], v[102:105]
	v_mfma_f32_16x16x32_bf16 v[86:89], v[166:169], v[202:205], v[86:89]
	v_mfma_f32_16x16x32_bf16 v[82:85], v[174:177], v[202:205], v[82:85]
	v_mfma_f32_16x16x32_bf16 v[66:69], v[174:177], v[232:235], v[66:69]
	v_mfma_f32_16x16x32_bf16 v[70:73], v[166:169], v[232:235], v[70:73]
	s_setprio 0
	s_barrier
; #define PG8_STAGE(bufoff, gbase, voff) do { _Pragma("unroll") for (int _i = 0; _i < 2; ++_i) \
;         __builtin_amdgcn_global_load_lds((const unsigned*)((const char*)(gbase) + (voff)[_i]), (LAS unsigned*)(lds + (bufoff) + ldsw + _i * 8192), 16, 0, 0); } while (0)
; #define PG8_LDA(dst, b, h) do { _Pragma("unroll") for (int m = 0; m < 4; ++m) _Pragma("unroll") for (int k = 0; k < 2; ++k) dst[m][k] = *(const LAS bf16x8*)(lds + PG8_SA(b, h) + aoff + m * 2048 + k * 1024); } while (0)
; #define PG8_MMA(ai, bj, At, Bt) do { __builtin_amdgcn_s_setprio(1); _Pragma("unroll") for (int m = 0; m < 4; ++m) _Pragma("unroll") for (int n = 0; n < 2; ++n) _Pragma("unroll") for (int k = 0; k < 2; ++k) \
;         acc[ai][bj][m][n] = __builtin_amdgcn_mfma_f32_16x16x32_bf16(Bt[n][k], At[m][k], acc[ai][bj][m][n], 0, 0, 0); __builtin_amdgcn_s_setprio(0); } while (0)
; #define PG8_WAIT_V(n) asm volatile("s_waitcnt vmcnt(" #n ")" ::: "memory")
; #define PG8_WAIT_L(n) asm volatile("s_waitcnt lgkmcnt(" #n ")" ::: "memory")
; #define PG8_BAR __builtin_amdgcn_s_barrier()
; #define PG8_SCHED __builtin_amdgcn_sched_barrier(0)
; template <class Epi>
; __device__ __forceinline__ void gemm_phase(LAS unsigned char* lds, const Gemm g, const StaticOrder& S, const Epi& E) {
;     ...
;             PG8_LDA(At, 1, 1); PG8_STAGE(PG8_SB(1, 0), b3, voffB); PG8_STAGE(PG8_SB(1, 1), b3 + hB, voffB); PG8_STAGE(PG8_SA(1, 0), a3, voffA);
;             PG8_WAIT_V(8); PG8_WAIT_L(0); PG8_BAR; PG8_MMA(1, 0, At, B0); PG8_MMA(1, 1, At, B1); PG8_BAR; PG8_SCHED;
;         }
	s_add_i32 s35, s35, s50
	v_lshl_add_u64 v[178:179], v[178:179], 0, s[88:89]
	s_mov_b32 m0, s35
	ds_read_b128 v[182:185], v211 offset:49152
	ds_read_b128 v[186:189], v211 offset:50176
	ds_read_b128 v[190:193], v211 offset:51200
	ds_read_b128 v[194:197], v211 offset:52224
	ds_read_b128 v[198:201], v211 offset:53248
	ds_read_b128 v[202:205], v211 offset:54272
	ds_read_b128 v[216:219], v211 offset:55296
	ds_read_b128 v[232:235], v211 offset:56320
	global_load_lds_dwordx4 v[178:179], off
	s_add_i32 m0, s35, 0x2000
	s_add_u32 s10, s10, 0x40080
	v_lshl_add_u64 v[178:179], v[206:207], 0, s[88:89]
	s_addc_u32 s11, s11, 0
	s_add_i32 s35, s42, s50
	global_load_lds_dwordx4 v[178:179], off
	v_lshl_add_u64 v[178:179], s[10:11], 0, v[132:133]
	s_mov_b32 m0, s35
	s_nop 0
	global_load_lds_dwordx4 v[178:179], off
	v_lshl_add_u64 v[178:179], s[10:11], 0, v[136:137]
	s_add_i32 m0, s35, 0x2000
	s_nop 0
	global_load_lds_dwordx4 v[178:179], off
	v_lshl_add_u64 v[178:179], v[220:221], 0, s[88:89]
	s_mov_b32 m0, s55
	s_nop 0
	global_load_lds_dwordx4 v[178:179], off
	v_lshl_add_u64 v[178:179], v[236:237], 0, s[88:89]
	s_mov_b32 m0, s56
	s_nop 0
	global_load_lds_dwordx4 v[178:179], off
	s_waitcnt vmcnt(8)
	s_waitcnt lgkmcnt(0)
	s_barrier
	s_setprio 1
	v_mfma_f32_16x16x32_bf16 v[62:65], v[146:149], v[182:185], v[62:65]
	v_mfma_f32_16x16x32_bf16 v[58:61], v[154:157], v[182:185], v[58:61]
	v_mfma_f32_16x16x32_bf16 v[42:45], v[154:157], v[190:193], v[42:45]
	v_mfma_f32_16x16x32_bf16 v[46:49], v[146:149], v[190:193], v[46:49]
	v_mfma_f32_16x16x32_bf16 v[30:33], v[146:149], v[198:201], v[30:33]
	v_mfma_f32_16x16x32_bf16 v[26:29], v[154:157], v[198:201], v[26:29]
	v_mfma_f32_16x16x32_bf16 v[10:13], v[154:157], v[216:219], v[10:13]
	v_mfma_f32_16x16x32_bf16 v[14:17], v[146:149], v[216:219], v[14:17]
	v_mfma_f32_16x16x32_bf16 v[62:65], v[150:153], v[186:189], v[62:65]
	v_mfma_f32_16x16x32_bf16 v[58:61], v[158:161], v[186:189], v[58:61]
	v_mfma_f32_16x16x32_bf16 v[42:45], v[158:161], v[194:197], v[42:45]
	v_mfma_f32_16x16x32_bf16 v[46:49], v[150:153], v[194:197], v[46:49]
	v_mfma_f32_16x16x32_bf16 v[30:33], v[150:153], v[202:205], v[30:33]
	v_mfma_f32_16x16x32_bf16 v[26:29], v[158:161], v[202:205], v[26:29]
	v_mfma_f32_16x16x32_bf16 v[10:13], v[158:161], v[232:235], v[10:13]
	v_mfma_f32_16x16x32_bf16 v[14:17], v[150:153], v[232:235], v[14:17]
	v_mfma_f32_16x16x32_bf16 v[54:57], v[162:165], v[182:185], v[54:57]
	v_mfma_f32_16x16x32_bf16 v[50:53], v[170:173], v[182:185], v[50:53]
	v_mfma_f32_16x16x32_bf16 v[34:37], v[170:173], v[190:193], v[34:37]
	v_mfma_f32_16x16x32_bf16 v[38:41], v[162:165], v[190:193], v[38:41]
	v_mfma_f32_16x16x32_bf16 v[22:25], v[162:165], v[198:201], v[22:25]
	v_mfma_f32_16x16x32_bf16 v[18:21], v[170:173], v[198:201], v[18:21]
	v_mfma_f32_16x16x32_bf16 v[2:5], v[170:173], v[216:219], v[2:5]
	v_mfma_f32_16x16x32_bf16 v[6:9], v[162:165], v[216:219], v[6:9]
	v_mfma_f32_16x16x32_bf16 v[54:57], v[166:169], v[186:189], v[54:57]
	v_mfma_f32_16x16x32_bf16 v[50:53], v[174:177], v[186:189], v[50:53]
	v_mfma_f32_16x16x32_bf16 v[34:37], v[174:177], v[194:197], v[34:37]
	v_mfma_f32_16x16x32_bf16 v[38:41], v[166:169], v[194:197], v[38:41]
	v_mfma_f32_16x16x32_bf16 v[22:25], v[166:169], v[202:205], v[22:25]
	v_mfma_f32_16x16x32_bf16 v[18:21], v[174:177], v[202:205], v[18:21]
	v_mfma_f32_16x16x32_bf16 v[2:5], v[174:177], v[232:235], v[2:5]
	v_mfma_f32_16x16x32_bf16 v[6:9], v[166:169], v[232:235], v[6:9]
	s_setprio 0
	s_barrier
	s_add_i32 s31, s31, 2
	s_add_u32 s8, s8, 0x100
	s_addc_u32 s9, s9, 0
	s_add_u32 s27, s27, 0x100
	s_addc_u32 s29, s29, 0
	s_cmp_gt_u32 s31, 13
	s_cbranch_scc0 .LBB0_1398
	s_and_b64 vcc, exec, s[16:17]
	s_cbranch_vccz .LBB0_1401
	s_barrier

; #define PG8_STAGE(bufoff, gbase, voff) do { _Pragma("unroll") for (int _i = 0; _i < 2; ++_i) \
;         __builtin_amdgcn_global_load_lds((const unsigned*)((const char*)(gbase) + (voff)[_i]), (LAS unsigned*)(lds + (bufoff) + ldsw + _i * 8192), 16, 0, 0); } while (0)
; #define PG8_LDA(dst, b, h) do { _Pragma("unroll") for (int m = 0; m < 4; ++m) _Pragma("unroll") for (int k = 0; k < 2; ++k) dst[m][k] = *(const LAS bf16x8*)(lds + PG8_SA(b, h) + aoff + m * 2048 + k * 1024); } while (0)
; #define PG8_LDB(dst, b, h) do { _Pragma("unroll") for (int n = 0; n < 2; ++n) _Pragma("unroll") for (int k = 0; k < 2; ++k) dst[n][k] = *(const LAS bf16x8*)(lds + PG8_SB(b, h) + boff + n * 2048 + k * 1024); } while (0)
; #define PG8_MMA(ai, bj, At, Bt) do { __builtin_amdgcn_s_setprio(1); _Pragma("unroll") for (int m = 0; m < 4; ++m) _Pragma("unroll") for (int n = 0; n < 2; ++n) _Pragma("unroll") for (int k = 0; k < 2; ++k) \
;         acc[ai][bj][m][n] = __builtin_amdgcn_mfma_f32_16x16x32_bf16(Bt[n][k], At[m][k], acc[ai][bj][m][n], 0, 0, 0); __builtin_amdgcn_s_setprio(0); } while (0)
; #define PG8_WAIT_V(n) asm volatile("s_waitcnt vmcnt(" #n ")" ::: "memory")
; #define PG8_WAIT_L(n) asm volatile("s_waitcnt lgkmcnt(" #n ")" ::: "memory")
; #define PG8_BAR __builtin_amdgcn_s_barrier()
; #define PG8_SCHED __builtin_amdgcn_sched_barrier(0)
; template <class Epi>
; __device__ __forceinline__ void gemm_phase(LAS unsigned char* lds, const Gemm g, const StaticOrder& S, const Epi& E) {
;     ...
;         for (int t = 0; t < nt; t += 2) {
;             const bool last = (t == nt - 2);
;             const char* a1 = cA + (size_t)(t + 1) * kstep;
;             const char* a2 = last ? nA : cA + (size_t)(t + 2) * kstep; const char* b2 = last ? nB : cB + (size_t)(t + 2) * kstep;
;             const char* a3 = a2 + kstep; const char* b3 = b2 + kstep;
;             PG8_LDB(B0, 0, 0); PG8_LDB(B1, 0, 1); PG8_SCHED; PG8_LDA(At, 0, 0); PG8_STAGE(PG8_SA(1, 1), a1 + hA, voffA);
;             PG8_WAIT_V(8); PG8_WAIT_L(0); PG8_BAR; PG8_MMA(0, 0, At, B0); PG8_MMA(0, 1, At, B1); PG8_BAR; PG8_SCHED;
;             PG8_LDA(At, 0, 1); PG8_STAGE(PG8_SB(0, 0), b2, voffB); PG8_STAGE(PG8_SB(0, 1), b2 + hB, voffB); PG8_STAGE(PG8_SA(0, 0), a2, voffA);
;             PG8_WAIT_V(8); PG8_WAIT_L(0); PG8_BAR; PG8_MMA(1, 0, At, B0); PG8_MMA(1, 1, At, B1); PG8_BAR; PG8_SCHED;
.LBB0_1550:
	s_add_u32 s22, s20, 0xfffc0080
	s_addc_u32 s23, s21, -1
	s_add_i32 s51, 0, 0x10000
	s_cmp_eq_u32 s50, 12
	s_cselect_b32 s25, s15, s23
	s_cselect_b32 s24, s46, s22
	v_add_u32_e32 v142, s51, v143
	s_cselect_b32 s23, s13, s49
	s_cselect_b32 s22, s47, s48
	s_add_i32 s54, 0, 0x14000
	ds_read_b128 v[148:151], v142
	ds_read_b128 v[152:155], v142 offset:1024
	ds_read_b128 v[156:159], v142 offset:2048
	ds_read_b128 v[160:163], v142 offset:3072
	v_add_u32_e32 v142, s54, v143
	ds_read_b128 v[164:167], v142
	ds_read_b128 v[168:171], v142 offset:1024
	ds_read_b128 v[172:175], v142 offset:2048
	ds_read_b128 v[176:179], v142 offset:3072
	v_lshl_add_u64 v[214:215], s[20:21], 0, v[138:139]
	s_add_i32 m0, s34, 0xc000
	ds_read_b128 v[182:185], v147
	ds_read_b128 v[186:189], v147 offset:1024
	ds_read_b128 v[190:193], v147 offset:2048
	ds_read_b128 v[194:197], v147 offset:3072
	ds_read_b128 v[198:201], v147 offset:4096
	ds_read_b128 v[202:205], v147 offset:5120
	ds_read_b128 v[206:209], v147 offset:6144
	ds_read_b128 v[210:213], v147 offset:7168
	global_load_lds_dwordx4 v[214:215], off
	v_lshl_add_u64 v[214:215], s[20:21], 0, v[140:141]
	s_add_i32 m0, s34, 0xe000
	s_nop 0
	global_load_lds_dwordx4 v[214:215], off
	s_waitcnt vmcnt(8)
	s_waitcnt lgkmcnt(0)
	s_barrier
	s_setprio 1
	v_mfma_f32_16x16x32_bf16 v[126:129], v[148:151], v[182:185], v[126:129]
	v_mfma_f32_16x16x32_bf16 v[122:125], v[156:159], v[182:185], v[122:125]
	v_mfma_f32_16x16x32_bf16 v[106:109], v[156:159], v[190:193], v[106:109]
	v_mfma_f32_16x16x32_bf16 v[110:113], v[148:151], v[190:193], v[110:113]
	v_mfma_f32_16x16x32_bf16 v[94:97], v[148:151], v[198:201], v[94:97]
	v_mfma_f32_16x16x32_bf16 v[90:93], v[156:159], v[198:201], v[90:93]
	v_mfma_f32_16x16x32_bf16 v[74:77], v[156:159], v[206:209], v[74:77]
	v_mfma_f32_16x16x32_bf16 v[78:81], v[148:151], v[206:209], v[78:81]
	v_mfma_f32_16x16x32_bf16 v[126:129], v[152:155], v[186:189], v[126:129]
	v_mfma_f32_16x16x32_bf16 v[122:125], v[160:163], v[186:189], v[122:125]
	v_mfma_f32_16x16x32_bf16 v[106:109], v[160:163], v[194:197], v[106:109]
	v_mfma_f32_16x16x32_bf16 v[110:113], v[152:155], v[194:197], v[110:113]
	v_mfma_f32_16x16x32_bf16 v[94:97], v[152:155], v[202:205], v[94:97]
	v_mfma_f32_16x16x32_bf16 v[90:93], v[160:163], v[202:205], v[90:93]
	v_mfma_f32_16x16x32_bf16 v[74:77], v[160:163], v[210:213], v[74:77]
	v_mfma_f32_16x16x32_bf16 v[78:81], v[152:155], v[210:213], v[78:81]
	v_mfma_f32_16x16x32_bf16 v[118:121], v[164:167], v[182:185], v[118:121]
	v_mfma_f32_16x16x32_bf16 v[114:117], v[172:175], v[182:185], v[114:117]
	v_mfma_f32_16x16x32_bf16 v[98:101], v[172:175], v[190:193], v[98:101]
	v_mfma_f32_16x16x32_bf16 v[102:105], v[164:167], v[190:193], v[102:105]
	v_mfma_f32_16x16x32_bf16 v[86:89], v[164:167], v[198:201], v[86:89]
	v_mfma_f32_16x16x32_bf16 v[82:85], v[172:175], v[198:201], v[82:85]
	v_mfma_f32_16x16x32_bf16 v[66:69], v[172:175], v[206:209], v[66:69]
	v_mfma_f32_16x16x32_bf16 v[70:73], v[164:167], v[206:209], v[70:73]
	v_mfma_f32_16x16x32_bf16 v[118:121], v[168:171], v[186:189], v[118:121]
	v_mfma_f32_16x16x32_bf16 v[114:117], v[176:179], v[186:189], v[114:117]
	v_mfma_f32_16x16x32_bf16 v[98:101], v[176:179], v[194:197], v[98:101]
	v_mfma_f32_16x16x32_bf16 v[102:105], v[168:171], v[194:197], v[102:105]
	v_mfma_f32_16x16x32_bf16 v[86:89], v[168:171], v[202:205], v[86:89]
	v_mfma_f32_16x16x32_bf16 v[82:85], v[176:179], v[202:205], v[82:85]
	v_mfma_f32_16x16x32_bf16 v[66:69], v[176:179], v[210:213], v[66:69]
	v_mfma_f32_16x16x32_bf16 v[70:73], v[168:171], v[210:213], v[70:73]
	s_setprio 0
	s_barrier
	s_add_i32 s51, s51, s31
	v_lshl_add_u64 v[214:215], s[22:23], 0, v[134:135]
	s_mov_b32 m0, s51
	ds_read_b128 v[182:185], v147 offset:16384
	ds_read_b128 v[186:189], v147 offset:17408
	ds_read_b128 v[190:193], v147 offset:18432
	ds_read_b128 v[194:197], v147 offset:19456
	ds_read_b128 v[198:201], v147 offset:20480
	ds_read_b128 v[202:205], v147 offset:21504
	ds_read_b128 v[206:209], v147 offset:22528
	ds_read_b128 v[210:213], v147 offset:23552
	global_load_lds_dwordx4 v[214:215], off
	s_add_i32 m0, s51, 0x2000
	s_add_u32 s52, s22, 0x40000
	v_lshl_add_u64 v[216:217], s[22:23], 0, v[130:131]
	s_addc_u32 s53, s23, 0
	s_add_i32 s51, s54, s31
	global_load_lds_dwordx4 v[216:217], off
	v_lshl_add_u64 v[218:219], s[52:53], 0, v[134:135]
	s_mov_b32 m0, s51
	v_lshl_add_u64 v[220:221], s[24:25], 0, v[132:133]
	global_load_lds_dwordx4 v[218:219], off
	v_lshl_add_u64 v[218:219], s[52:53], 0, v[130:131]
	s_add_i32 m0, s51, 0x2000
	s_nop 0
	global_load_lds_dwordx4 v[218:219], off
	v_lshl_add_u64 v[218:219], s[24:25], 0, v[136:137]
	s_mov_b32 m0, s34
	s_nop 0
	global_load_lds_dwordx4 v[218:219], off
	s_mov_b32 m0, s35
	s_nop 0
	global_load_lds_dwordx4 v[220:221], off
	s_waitcnt vmcnt(8)
	s_waitcnt lgkmcnt(0)
	s_barrier
; #define PG8_STAGE(bufoff, gbase, voff) do { _Pragma("unroll") for (int _i = 0; _i < 2; ++_i) \
;         __builtin_amdgcn_global_load_lds((const unsigned*)((const char*)(gbase) + (voff)[_i]), (LAS unsigned*)(lds + (bufoff) + ldsw + _i * 8192), 16, 0, 0); } while (0)
; #define PG8_LDA(dst, b, h) do { _Pragma("unroll") for (int m = 0; m < 4; ++m) _Pragma("unroll") for (int k = 0; k < 2; ++k) dst[m][k] = *(const LAS bf16x8*)(lds + PG8_SA(b, h) + aoff + m * 2048 + k * 1024); } while (0)
; #define PG8_LDB(dst, b, h) do { _Pragma("unroll") for (int n = 0; n < 2; ++n) _Pragma("unroll") for (int k = 0; k < 2; ++k) dst[n][k] = *(const LAS bf16x8*)(lds + PG8_SB(b, h) + boff + n * 2048 + k * 1024); } while (0)
; #define PG8_MMA(ai, bj, At, Bt) do { __builtin_amdgcn_s_setprio(1); _Pragma("unroll") for (int m = 0; m < 4; ++m) _Pragma("unroll") for (int n = 0; n < 2; ++n) _Pragma("unroll") for (int k = 0; k < 2; ++k) \
;         acc[ai][bj][m][n] = __builtin_amdgcn_mfma_f32_16x16x32_bf16(Bt[n][k], At[m][k], acc[ai][bj][m][n], 0, 0, 0); __builtin_amdgcn_s_setprio(0); } while (0)
; #define PG8_WAIT_V(n) asm volatile("s_waitcnt vmcnt(" #n ")" ::: "memory")
; #define PG8_WAIT_L(n) asm volatile("s_waitcnt lgkmcnt(" #n ")" ::: "memory")
; #define PG8_BAR __builtin_amdgcn_s_barrier()
; #define PG8_SCHED __builtin_amdgcn_sched_barrier(0)
; template <class Epi>
; __device__ __forceinline__ void gemm_phase(LAS unsigned char* lds, const Gemm g, const StaticOrder& S, const Epi& E) {
;     ...
;             PG8_WAIT_V(8); PG8_WAIT_L(0); PG8_BAR; PG8_MMA(1, 0, At, B0); PG8_MMA(1, 1, At, B1); PG8_BAR; PG8_SCHED;
;             PG8_LDB(B0, 1, 0); PG8_LDB(B1, 1, 1); PG8_SCHED; PG8_LDA(At, 1, 0); PG8_STAGE(PG8_SA(0, 1), a2 + hA, voffA);
;             PG8_WAIT_V(8); PG8_WAIT_L(0); PG8_BAR; PG8_MMA(0, 0, At, B0); PG8_MMA(0, 1, At, B1); PG8_BAR; PG8_SCHED;
	s_setprio 1
	v_mfma_f32_16x16x32_bf16 v[62:65], v[148:151], v[182:185], v[62:65]
	v_mfma_f32_16x16x32_bf16 v[58:61], v[156:159], v[182:185], v[58:61]
	v_mfma_f32_16x16x32_bf16 v[42:45], v[156:159], v[190:193], v[42:45]
	v_mfma_f32_16x16x32_bf16 v[46:49], v[148:151], v[190:193], v[46:49]
	v_mfma_f32_16x16x32_bf16 v[30:33], v[148:151], v[198:201], v[30:33]
	v_mfma_f32_16x16x32_bf16 v[26:29], v[156:159], v[198:201], v[26:29]
	v_mfma_f32_16x16x32_bf16 v[10:13], v[156:159], v[206:209], v[10:13]
	v_mfma_f32_16x16x32_bf16 v[14:17], v[148:151], v[206:209], v[14:17]
	v_mfma_f32_16x16x32_bf16 v[62:65], v[152:155], v[186:189], v[62:65]
	v_mfma_f32_16x16x32_bf16 v[58:61], v[160:163], v[186:189], v[58:61]
	v_mfma_f32_16x16x32_bf16 v[42:45], v[160:163], v[194:197], v[42:45]
	v_mfma_f32_16x16x32_bf16 v[46:49], v[152:155], v[194:197], v[46:49]
	v_mfma_f32_16x16x32_bf16 v[30:33], v[152:155], v[202:205], v[30:33]
	v_mfma_f32_16x16x32_bf16 v[26:29], v[160:163], v[202:205], v[26:29]
	v_mfma_f32_16x16x32_bf16 v[10:13], v[160:163], v[210:213], v[10:13]
	v_mfma_f32_16x16x32_bf16 v[14:17], v[152:155], v[210:213], v[14:17]
	v_mfma_f32_16x16x32_bf16 v[54:57], v[164:167], v[182:185], v[54:57]
	v_mfma_f32_16x16x32_bf16 v[50:53], v[172:175], v[182:185], v[50:53]
	v_mfma_f32_16x16x32_bf16 v[34:37], v[172:175], v[190:193], v[34:37]
	v_mfma_f32_16x16x32_bf16 v[38:41], v[164:167], v[190:193], v[38:41]
	v_mfma_f32_16x16x32_bf16 v[22:25], v[164:167], v[198:201], v[22:25]
	v_mfma_f32_16x16x32_bf16 v[18:21], v[172:175], v[198:201], v[18:21]
	v_mfma_f32_16x16x32_bf16 v[2:5], v[172:175], v[206:209], v[2:5]
	v_mfma_f32_16x16x32_bf16 v[6:9], v[164:167], v[206:209], v[6:9]
	v_mfma_f32_16x16x32_bf16 v[54:57], v[168:171], v[186:189], v[54:57]
	v_mfma_f32_16x16x32_bf16 v[50:53], v[176:179], v[186:189], v[50:53]
	v_mfma_f32_16x16x32_bf16 v[34:37], v[176:179], v[194:197], v[34:37]
	v_mfma_f32_16x16x32_bf16 v[38:41], v[168:171], v[194:197], v[38:41]
	v_mfma_f32_16x16x32_bf16 v[22:25], v[168:171], v[202:205], v[22:25]
	v_mfma_f32_16x16x32_bf16 v[18:21], v[176:179], v[202:205], v[18:21]
	v_mfma_f32_16x16x32_bf16 v[2:5], v[176:179], v[210:213], v[2:5]
	v_mfma_f32_16x16x32_bf16 v[6:9], v[168:171], v[210:213], v[6:9]
	s_setprio 0
	s_barrier
	s_add_i32 s51, 0, 0x18000
	v_add_u32_e32 v142, s51, v143
	s_add_i32 s52, 0, 0x1c000
	ds_read_b128 v[148:151], v142
	ds_read_b128 v[152:155], v142 offset:1024
	ds_read_b128 v[156:159], v142 offset:2048
	ds_read_b128 v[160:163], v142 offset:3072
	v_add_u32_e32 v142, s52, v143
	ds_read_b128 v[164:167], v142
	ds_read_b128 v[168:171], v142 offset:1024
	ds_read_b128 v[172:175], v142 offset:2048
	ds_read_b128 v[176:179], v142 offset:3072
	s_add_u32 s24, s24, 0x40000
	s_addc_u32 s25, s25, 0
	s_mov_b32 m0, s36
	v_lshl_add_u64 v[232:233], s[24:25], 0, v[136:137]
	ds_read_b128 v[182:185], v147 offset:32768
	ds_read_b128 v[186:189], v147 offset:33792
	ds_read_b128 v[190:193], v147 offset:34816
	ds_read_b128 v[194:197], v147 offset:35840
	ds_read_b128 v[198:201], v147 offset:36864
	ds_read_b128 v[202:205], v147 offset:37888
	ds_read_b128 v[206:209], v147 offset:38912
	ds_read_b128 v[210:213], v147 offset:39936
	global_load_lds_dwordx4 v[232:233], off
	v_lshl_add_u64 v[232:233], s[24:25], 0, v[132:133]
	s_mov_b32 m0, s37
	s_nop 0
	global_load_lds_dwordx4 v[232:233], off
	s_waitcnt vmcnt(8)
	s_waitcnt lgkmcnt(0)
	s_barrier
	s_setprio 1
	v_mfma_f32_16x16x32_bf16 v[126:129], v[148:151], v[182:185], v[126:129]
	v_mfma_f32_16x16x32_bf16 v[122:125], v[156:159], v[182:185], v[122:125]
	v_mfma_f32_16x16x32_bf16 v[106:109], v[156:159], v[190:193], v[106:109]
	v_mfma_f32_16x16x32_bf16 v[110:113], v[148:151], v[190:193], v[110:113]
	v_mfma_f32_16x16x32_bf16 v[94:97], v[148:151], v[198:201], v[94:97]
	v_mfma_f32_16x16x32_bf16 v[90:93], v[156:159], v[198:201], v[90:93]
	v_mfma_f32_16x16x32_bf16 v[74:77], v[156:159], v[206:209], v[74:77]
	v_mfma_f32_16x16x32_bf16 v[78:81], v[148:151], v[206:209], v[78:81]
	v_mfma_f32_16x16x32_bf16 v[126:129], v[152:155], v[186:189], v[126:129]
	v_mfma_f32_16x16x32_bf16 v[122:125], v[160:163], v[186:189], v[122:125]
	v_mfma_f32_16x16x32_bf16 v[106:109], v[160:163], v[194:197], v[106:109]
	v_mfma_f32_16x16x32_bf16 v[110:113], v[152:155], v[194:197], v[110:113]
	v_mfma_f32_16x16x32_bf16 v[94:97], v[152:155], v[202:205], v[94:97]
	v_mfma_f32_16x16x32_bf16 v[90:93], v[160:163], v[202:205], v[90:93]
	v_mfma_f32_16x16x32_bf16 v[74:77], v[160:163], v[210:213], v[74:77]
	v_mfma_f32_16x16x32_bf16 v[78:81], v[152:155], v[210:213], v[78:81]
	v_mfma_f32_16x16x32_bf16 v[118:121], v[164:167], v[182:185], v[118:121]
	v_mfma_f32_16x16x32_bf16 v[114:117], v[172:175], v[182:185], v[114:117]
	v_mfma_f32_16x16x32_bf16 v[98:101], v[172:175], v[190:193], v[98:101]
	v_mfma_f32_16x16x32_bf16 v[102:105], v[164:167], v[190:193], v[102:105]
	v_mfma_f32_16x16x32_bf16 v[86:89], v[164:167], v[198:201], v[86:89]
	v_mfma_f32_16x16x32_bf16 v[82:85], v[172:175], v[198:201], v[82:85]
	v_mfma_f32_16x16x32_bf16 v[66:69], v[172:175], v[206:209], v[66:69]
	v_mfma_f32_16x16x32_bf16 v[70:73], v[164:167], v[206:209], v[70:73]
	v_mfma_f32_16x16x32_bf16 v[118:121], v[168:171], v[186:189], v[118:121]
	v_mfma_f32_16x16x32_bf16 v[114:117], v[176:179], v[186:189], v[114:117]
	v_mfma_f32_16x16x32_bf16 v[98:101], v[176:179], v[194:197], v[98:101]
	v_mfma_f32_16x16x32_bf16 v[102:105], v[168:171], v[194:197], v[102:105]
	v_mfma_f32_16x16x32_bf16 v[86:89], v[168:171], v[202:205], v[86:89]
	v_mfma_f32_16x16x32_bf16 v[82:85], v[176:179], v[202:205], v[82:85]
	v_mfma_f32_16x16x32_bf16 v[66:69], v[176:179], v[210:213], v[66:69]
	v_mfma_f32_16x16x32_bf16 v[70:73], v[168:171], v[210:213], v[70:73]
	s_setprio 0
	s_barrier
; #define PG8_STAGE(bufoff, gbase, voff) do { _Pragma("unroll") for (int _i = 0; _i < 2; ++_i) \
;         __builtin_amdgcn_global_load_lds((const unsigned*)((const char*)(gbase) + (voff)[_i]), (LAS unsigned*)(lds + (bufoff) + ldsw + _i * 8192), 16, 0, 0); } while (0)
; #define PG8_LDA(dst, b, h) do { _Pragma("unroll") for (int m = 0; m < 4; ++m) _Pragma("unroll") for (int k = 0; k < 2; ++k) dst[m][k] = *(const LAS bf16x8*)(lds + PG8_SA(b, h) + aoff + m * 2048 + k * 1024); } while (0)
; #define PG8_MMA(ai, bj, At, Bt) do { __builtin_amdgcn_s_setprio(1); _Pragma("unroll") for (int m = 0; m < 4; ++m) _Pragma("unroll") for (int n = 0; n < 2; ++n) _Pragma("unroll") for (int k = 0; k < 2; ++k) \
;         acc[ai][bj][m][n] = __builtin_amdgcn_mfma_f32_16x16x32_bf16(Bt[n][k], At[m][k], acc[ai][bj][m][n], 0, 0, 0); __builtin_amdgcn_s_setprio(0); } while (0)
; #define PG8_WAIT_V(n) asm volatile("s_waitcnt vmcnt(" #n ")" ::: "memory")
; #define PG8_WAIT_L(n) asm volatile("s_waitcnt lgkmcnt(" #n ")" ::: "memory")
; #define PG8_BAR __builtin_amdgcn_s_barrier()
; #define PG8_SCHED __builtin_amdgcn_sched_barrier(0)
; template <class Epi>
; __device__ __forceinline__ void gemm_phase(LAS unsigned char* lds, const Gemm g, const StaticOrder& S, const Epi& E) {
;     ...
;             PG8_LDA(At, 1, 1); PG8_STAGE(PG8_SB(1, 0), b3, voffB); PG8_STAGE(PG8_SB(1, 1), b3 + hB, voffB); PG8_STAGE(PG8_SA(1, 0), a3, voffA);
;             PG8_WAIT_V(8); PG8_WAIT_L(0); PG8_BAR; PG8_MMA(1, 0, At, B0); PG8_MMA(1, 1, At, B1); PG8_BAR; PG8_SCHED;
;         }
	s_add_i32 s24, s51, s31
	v_lshl_add_u64 v[214:215], v[214:215], 0, s[88:89]
	s_mov_b32 m0, s24
	ds_read_b128 v[182:185], v147 offset:49152
	ds_read_b128 v[186:189], v147 offset:50176
	ds_read_b128 v[190:193], v147 offset:51200
	ds_read_b128 v[194:197], v147 offset:52224
	ds_read_b128 v[198:201], v147 offset:53248
	ds_read_b128 v[202:205], v147 offset:54272
	ds_read_b128 v[206:209], v147 offset:55296
	ds_read_b128 v[210:213], v147 offset:56320
	global_load_lds_dwordx4 v[214:215], off
	s_add_i32 m0, s24, 0x2000
	s_add_u32 s22, s22, 0x40080
	v_lshl_add_u64 v[214:215], v[216:217], 0, s[88:89]
	s_addc_u32 s23, s23, 0
	s_add_i32 s24, s52, s31
	global_load_lds_dwordx4 v[214:215], off
	v_lshl_add_u64 v[214:215], s[22:23], 0, v[134:135]
	s_mov_b32 m0, s24
	s_nop 0
	global_load_lds_dwordx4 v[214:215], off
	v_lshl_add_u64 v[214:215], s[22:23], 0, v[130:131]
	s_add_i32 m0, s24, 0x2000
	s_nop 0
	global_load_lds_dwordx4 v[214:215], off
	v_lshl_add_u64 v[214:215], v[218:219], 0, s[88:89]
	s_mov_b32 m0, s38
	s_nop 0
	global_load_lds_dwordx4 v[214:215], off
	v_lshl_add_u64 v[214:215], v[220:221], 0, s[88:89]
	s_mov_b32 m0, s39
	s_nop 0
	global_load_lds_dwordx4 v[214:215], off
	s_waitcnt vmcnt(8)
	s_waitcnt lgkmcnt(0)
	s_barrier
	s_setprio 1
	v_mfma_f32_16x16x32_bf16 v[62:65], v[148:151], v[182:185], v[62:65]
	v_mfma_f32_16x16x32_bf16 v[58:61], v[156:159], v[182:185], v[58:61]
	v_mfma_f32_16x16x32_bf16 v[42:45], v[156:159], v[190:193], v[42:45]
	v_mfma_f32_16x16x32_bf16 v[46:49], v[148:151], v[190:193], v[46:49]
	v_mfma_f32_16x16x32_bf16 v[30:33], v[148:151], v[198:201], v[30:33]
	v_mfma_f32_16x16x32_bf16 v[26:29], v[156:159], v[198:201], v[26:29]
	v_mfma_f32_16x16x32_bf16 v[10:13], v[156:159], v[206:209], v[10:13]
	v_mfma_f32_16x16x32_bf16 v[14:17], v[148:151], v[206:209], v[14:17]
	v_mfma_f32_16x16x32_bf16 v[62:65], v[152:155], v[186:189], v[62:65]
	v_mfma_f32_16x16x32_bf16 v[58:61], v[160:163], v[186:189], v[58:61]
	v_mfma_f32_16x16x32_bf16 v[42:45], v[160:163], v[194:197], v[42:45]
	v_mfma_f32_16x16x32_bf16 v[46:49], v[152:155], v[194:197], v[46:49]
	v_mfma_f32_16x16x32_bf16 v[30:33], v[152:155], v[202:205], v[30:33]
	v_mfma_f32_16x16x32_bf16 v[26:29], v[160:163], v[202:205], v[26:29]
	v_mfma_f32_16x16x32_bf16 v[10:13], v[160:163], v[210:213], v[10:13]
	v_mfma_f32_16x16x32_bf16 v[14:17], v[152:155], v[210:213], v[14:17]
	v_mfma_f32_16x16x32_bf16 v[54:57], v[164:167], v[182:185], v[54:57]
	v_mfma_f32_16x16x32_bf16 v[50:53], v[172:175], v[182:185], v[50:53]
	v_mfma_f32_16x16x32_bf16 v[34:37], v[172:175], v[190:193], v[34:37]
	v_mfma_f32_16x16x32_bf16 v[38:41], v[164:167], v[190:193], v[38:41]
	v_mfma_f32_16x16x32_bf16 v[22:25], v[164:167], v[198:201], v[22:25]
	v_mfma_f32_16x16x32_bf16 v[18:21], v[172:175], v[198:201], v[18:21]
	v_mfma_f32_16x16x32_bf16 v[2:5], v[172:175], v[206:209], v[2:5]
	v_mfma_f32_16x16x32_bf16 v[6:9], v[164:167], v[206:209], v[6:9]
	v_mfma_f32_16x16x32_bf16 v[54:57], v[168:171], v[186:189], v[54:57]
	v_mfma_f32_16x16x32_bf16 v[50:53], v[176:179], v[186:189], v[50:53]
	v_mfma_f32_16x16x32_bf16 v[34:37], v[176:179], v[194:197], v[34:37]
	v_mfma_f32_16x16x32_bf16 v[38:41], v[168:171], v[194:197], v[38:41]
	v_mfma_f32_16x16x32_bf16 v[22:25], v[168:171], v[202:205], v[22:25]
	v_mfma_f32_16x16x32_bf16 v[18:21], v[176:179], v[202:205], v[18:21]
	v_mfma_f32_16x16x32_bf16 v[2:5], v[176:179], v[210:213], v[2:5]
	v_mfma_f32_16x16x32_bf16 v[6:9], v[168:171], v[210:213], v[6:9]
	s_setprio 0
	s_barrier
	s_add_i32 s50, s50, 2
	s_add_u32 s20, s20, 0x100
	s_addc_u32 s21, s21, 0
	s_add_u32 s48, s48, 0x100
	s_addc_u32 s49, s49, 0
	s_cmp_gt_u32 s50, 13
	s_cbranch_scc0 .LBB0_1550
	s_and_b64 vcc, exec, s[10:11]
	s_cbranch_vccz .LBB0_1553
	s_barrier

; #define PG8_STAGE(bufoff, gbase, voff) do { _Pragma("unroll") for (int _i = 0; _i < 2; ++_i) \
;         __builtin_amdgcn_global_load_lds((const unsigned*)((const char*)(gbase) + (voff)[_i]), (LAS unsigned*)(lds + (bufoff) + ldsw + _i * 8192), 16, 0, 0); } while (0)
; #define PG8_LDA(dst, b, h) do { _Pragma("unroll") for (int m = 0; m < 4; ++m) _Pragma("unroll") for (int k = 0; k < 2; ++k) dst[m][k] = *(const LAS bf16x8*)(lds + PG8_SA(b, h) + aoff + m * 2048 + k * 1024); } while (0)
; #define PG8_LDB(dst, b, h) do { _Pragma("unroll") for (int n = 0; n < 2; ++n) _Pragma("unroll") for (int k = 0; k < 2; ++k) dst[n][k] = *(const LAS bf16x8*)(lds + PG8_SB(b, h) + boff + n * 2048 + k * 1024); } while (0)
; #define PG8_MMA(ai, bj, At, Bt) do { __builtin_amdgcn_s_setprio(1); _Pragma("unroll") for (int m = 0; m < 4; ++m) _Pragma("unroll") for (int n = 0; n < 2; ++n) _Pragma("unroll") for (int k = 0; k < 2; ++k) \
;         acc[ai][bj][m][n] = __builtin_amdgcn_mfma_f32_16x16x32_bf16(Bt[n][k], At[m][k], acc[ai][bj][m][n], 0, 0, 0); __builtin_amdgcn_s_setprio(0); } while (0)
; #define PG8_WAIT_V(n) asm volatile("s_waitcnt vmcnt(" #n ")" ::: "memory")
; #define PG8_WAIT_L(n) asm volatile("s_waitcnt lgkmcnt(" #n ")" ::: "memory")
; #define PG8_BAR __builtin_amdgcn_s_barrier()
; #define PG8_SCHED __builtin_amdgcn_sched_barrier(0)
; template <class Epi>
; __device__ __forceinline__ void gemm_phase(LAS unsigned char* lds, const Gemm g, const StaticOrder& S, const Epi& E) {
;     ...
;         for (int t = 0; t < nt; t += 2) {
;             const bool last = (t == nt - 2);
;             const char* a1 = cA + (size_t)(t + 1) * kstep;
;             const char* a2 = last ? nA : cA + (size_t)(t + 2) * kstep; const char* b2 = last ? nB : cB + (size_t)(t + 2) * kstep;
;             const char* a3 = a2 + kstep; const char* b3 = b2 + kstep;
;             PG8_LDB(B0, 0, 0); PG8_LDB(B1, 0, 1); PG8_SCHED; PG8_LDA(At, 0, 0); PG8_STAGE(PG8_SA(1, 1), a1 + hA, voffA);
;             PG8_WAIT_V(8); PG8_WAIT_L(0); PG8_BAR; PG8_MMA(0, 0, At, B0); PG8_MMA(0, 1, At, B1); PG8_BAR; PG8_SCHED;
;             PG8_LDA(At, 0, 1); PG8_STAGE(PG8_SB(0, 0), b2, voffB); PG8_STAGE(PG8_SB(0, 1), b2 + hB, voffB); PG8_STAGE(PG8_SA(0, 0), a2, voffA);
;             PG8_WAIT_V(8); PG8_WAIT_L(0); PG8_BAR; PG8_MMA(1, 0, At, B0); PG8_MMA(1, 1, At, B1); PG8_BAR; PG8_SCHED;
.LBB0_1632:
	s_add_u32 s8, s10, 0x100
	s_addc_u32 s9, s11, 0
	s_add_i32 s70, 0, 0x10000
	s_cmp_eq_u32 s67, 40
	s_cselect_b32 s45, s39, s9
	s_cselect_b32 s44, s38, s8
	s_cselect_b32 s43, s41, s37
	s_cselect_b32 s42, s40, s35
	s_add_i32 s71, 0, 0x14000
	s_waitcnt lgkmcnt(0)
	v_add_u32_e32 v158, s70, v180
	v_add_u32_e32 v174, s71, v180
	ds_read_b128 v[146:149], v158
	ds_read_b128 v[150:153], v158 offset:1024
	ds_read_b128 v[154:157], v158 offset:2048
	ds_read_b128 v[158:161], v158 offset:3072
	ds_read_b128 v[162:165], v174
	ds_read_b128 v[166:169], v174 offset:1024
	ds_read_b128 v[170:173], v174 offset:2048
	ds_read_b128 v[174:177], v174 offset:3072
	v_lshl_add_u64 v[178:179], s[10:11], 0, v[142:143]
	s_add_i32 m0, s52, 0xc000
	ds_read_b128 v[182:185], v192
	ds_read_b128 v[196:199], v192 offset:1024
	ds_read_b128 v[200:203], v192 offset:2048
	ds_read_b128 v[204:207], v192 offset:3072
	ds_read_b128 v[208:211], v192 offset:4096
	ds_read_b128 v[212:215], v192 offset:5120
	ds_read_b128 v[216:219], v192 offset:6144
	ds_read_b128 v[232:235], v192 offset:7168
	global_load_lds_dwordx4 v[178:179], off
	v_lshl_add_u64 v[178:179], s[10:11], 0, v[144:145]
	s_add_i32 m0, s52, 0xe000
	s_nop 0
	global_load_lds_dwordx4 v[178:179], off
	s_waitcnt vmcnt(8)
	s_waitcnt lgkmcnt(0)
	s_barrier
	s_setprio 1
	v_mfma_f32_16x16x32_bf16 v[26:29], v[146:149], v[182:185], v[26:29]
	v_mfma_f32_16x16x32_bf16 v[30:33], v[154:157], v[182:185], v[30:33]
	v_mfma_f32_16x16x32_bf16 v[62:65], v[154:157], v[200:203], v[62:65]
	v_mfma_f32_16x16x32_bf16 v[58:61], v[146:149], v[200:203], v[58:61]
	v_mfma_f32_16x16x32_bf16 v[90:93], v[146:149], v[208:211], v[90:93]
	v_mfma_f32_16x16x32_bf16 v[94:97], v[154:157], v[208:211], v[94:97]
	v_mfma_f32_16x16x32_bf16 v[118:121], v[154:157], v[216:219], v[118:121]
	v_mfma_f32_16x16x32_bf16 v[114:117], v[146:149], v[216:219], v[114:117]
	v_mfma_f32_16x16x32_bf16 v[26:29], v[150:153], v[196:199], v[26:29]
	v_mfma_f32_16x16x32_bf16 v[30:33], v[158:161], v[196:199], v[30:33]
	v_mfma_f32_16x16x32_bf16 v[62:65], v[158:161], v[204:207], v[62:65]
	v_mfma_f32_16x16x32_bf16 v[58:61], v[150:153], v[204:207], v[58:61]
	v_mfma_f32_16x16x32_bf16 v[90:93], v[150:153], v[212:215], v[90:93]
	v_mfma_f32_16x16x32_bf16 v[94:97], v[158:161], v[212:215], v[94:97]
	v_mfma_f32_16x16x32_bf16 v[118:121], v[158:161], v[232:235], v[118:121]
	v_mfma_f32_16x16x32_bf16 v[114:117], v[150:153], v[232:235], v[114:117]
	v_mfma_f32_16x16x32_bf16 v[42:45], v[162:165], v[182:185], v[42:45]
	v_mfma_f32_16x16x32_bf16 v[46:49], v[170:173], v[182:185], v[46:49]
	v_mfma_f32_16x16x32_bf16 v[78:81], v[170:173], v[200:203], v[78:81]
	v_mfma_f32_16x16x32_bf16 v[74:77], v[162:165], v[200:203], v[74:77]
	v_mfma_f32_16x16x32_bf16 v[106:109], v[162:165], v[208:211], v[106:109]
	v_mfma_f32_16x16x32_bf16 v[110:113], v[170:173], v[208:211], v[110:113]
	v_mfma_f32_16x16x32_bf16 v[122:125], v[170:173], v[216:219], v[122:125]
	v_mfma_f32_16x16x32_bf16 v[126:129], v[162:165], v[216:219], v[126:129]
	v_mfma_f32_16x16x32_bf16 v[42:45], v[166:169], v[196:199], v[42:45]
	v_mfma_f32_16x16x32_bf16 v[46:49], v[174:177], v[196:199], v[46:49]
	v_mfma_f32_16x16x32_bf16 v[78:81], v[174:177], v[204:207], v[78:81]
	v_mfma_f32_16x16x32_bf16 v[74:77], v[166:169], v[204:207], v[74:77]
	v_mfma_f32_16x16x32_bf16 v[106:109], v[166:169], v[212:215], v[106:109]
	v_mfma_f32_16x16x32_bf16 v[110:113], v[174:177], v[212:215], v[110:113]
	v_mfma_f32_16x16x32_bf16 v[122:125], v[174:177], v[232:235], v[122:125]
	v_mfma_f32_16x16x32_bf16 v[126:129], v[166:169], v[232:235], v[126:129]
	s_setprio 0
	s_barrier
	s_add_i32 s10, s70, s47
	v_lshl_add_u64 v[178:179], s[42:43], 0, v[132:133]
	s_mov_b32 m0, s10
	ds_read_b128 v[182:185], v192 offset:16384
	ds_read_b128 v[196:199], v192 offset:17408
	ds_read_b128 v[200:203], v192 offset:18432
	ds_read_b128 v[204:207], v192 offset:19456
	ds_read_b128 v[208:211], v192 offset:20480
	ds_read_b128 v[212:215], v192 offset:21504
	ds_read_b128 v[216:219], v192 offset:22528
	ds_read_b128 v[232:235], v192 offset:23552
	global_load_lds_dwordx4 v[178:179], off
	s_add_i32 m0, s10, 0x2000
	s_add_u32 s10, s42, 0xb0000
	v_lshl_add_u64 v[186:187], s[42:43], 0, v[136:137]
	s_addc_u32 s11, s43, 0
	s_add_i32 s70, s71, s47
	global_load_lds_dwordx4 v[186:187], off
	v_lshl_add_u64 v[220:221], s[10:11], 0, v[132:133]
	s_mov_b32 m0, s70
	v_lshl_add_u64 v[236:237], s[44:45], 0, v[134:135]
	global_load_lds_dwordx4 v[220:221], off
	v_lshl_add_u64 v[220:221], s[10:11], 0, v[136:137]
	s_add_i32 m0, s70, 0x2000
	s_nop 0
	global_load_lds_dwordx4 v[220:221], off
	v_lshl_add_u64 v[220:221], s[44:45], 0, v[130:131]
	s_mov_b32 m0, s52
	s_nop 0
	global_load_lds_dwordx4 v[220:221], off
	s_mov_b32 m0, s53
	s_nop 0
	global_load_lds_dwordx4 v[236:237], off
	s_waitcnt vmcnt(8)
	s_waitcnt lgkmcnt(0)
	s_barrier
; #define PG8_STAGE(bufoff, gbase, voff) do { _Pragma("unroll") for (int _i = 0; _i < 2; ++_i) \
;         __builtin_amdgcn_global_load_lds((const unsigned*)((const char*)(gbase) + (voff)[_i]), (LAS unsigned*)(lds + (bufoff) + ldsw + _i * 8192), 16, 0, 0); } while (0)
; #define PG8_LDA(dst, b, h) do { _Pragma("unroll") for (int m = 0; m < 4; ++m) _Pragma("unroll") for (int k = 0; k < 2; ++k) dst[m][k] = *(const LAS bf16x8*)(lds + PG8_SA(b, h) + aoff + m * 2048 + k * 1024); } while (0)
; #define PG8_LDB(dst, b, h) do { _Pragma("unroll") for (int n = 0; n < 2; ++n) _Pragma("unroll") for (int k = 0; k < 2; ++k) dst[n][k] = *(const LAS bf16x8*)(lds + PG8_SB(b, h) + boff + n * 2048 + k * 1024); } while (0)
; #define PG8_MMA(ai, bj, At, Bt) do { __builtin_amdgcn_s_setprio(1); _Pragma("unroll") for (int m = 0; m < 4; ++m) _Pragma("unroll") for (int n = 0; n < 2; ++n) _Pragma("unroll") for (int k = 0; k < 2; ++k) \
;         acc[ai][bj][m][n] = __builtin_amdgcn_mfma_f32_16x16x32_bf16(Bt[n][k], At[m][k], acc[ai][bj][m][n], 0, 0, 0); __builtin_amdgcn_s_setprio(0); } while (0)
; #define PG8_WAIT_V(n) asm volatile("s_waitcnt vmcnt(" #n ")" ::: "memory")
; #define PG8_WAIT_L(n) asm volatile("s_waitcnt lgkmcnt(" #n ")" ::: "memory")
; #define PG8_BAR __builtin_amdgcn_s_barrier()
; #define PG8_SCHED __builtin_amdgcn_sched_barrier(0)
; template <class Epi>
; __device__ __forceinline__ void gemm_phase(LAS unsigned char* lds, const Gemm g, const StaticOrder& S, const Epi& E) {
;     ...
;             PG8_WAIT_V(8); PG8_WAIT_L(0); PG8_BAR; PG8_MMA(1, 0, At, B0); PG8_MMA(1, 1, At, B1); PG8_BAR; PG8_SCHED;
;             PG8_LDB(B0, 1, 0); PG8_LDB(B1, 1, 1); PG8_SCHED; PG8_LDA(At, 1, 0); PG8_STAGE(PG8_SA(0, 1), a2 + hA, voffA);
;             PG8_WAIT_V(8); PG8_WAIT_L(0); PG8_BAR; PG8_MMA(0, 0, At, B0); PG8_MMA(0, 1, At, B1); PG8_BAR; PG8_SCHED;
	s_setprio 1
	v_mfma_f32_16x16x32_bf16 v[102:105], v[146:149], v[182:185], v[102:105]
	v_mfma_f32_16x16x32_bf16 v[98:101], v[154:157], v[182:185], v[98:101]
	v_mfma_f32_16x16x32_bf16 v[66:69], v[154:157], v[200:203], v[66:69]
	v_mfma_f32_16x16x32_bf16 v[70:73], v[146:149], v[200:203], v[70:73]
	v_mfma_f32_16x16x32_bf16 v[38:41], v[146:149], v[208:211], v[38:41]
	v_mfma_f32_16x16x32_bf16 v[34:37], v[154:157], v[208:211], v[34:37]
	v_mfma_f32_16x16x32_bf16 v[10:13], v[154:157], v[216:219], v[10:13]
	v_mfma_f32_16x16x32_bf16 v[14:17], v[146:149], v[216:219], v[14:17]
	v_mfma_f32_16x16x32_bf16 v[102:105], v[150:153], v[196:199], v[102:105]
	v_mfma_f32_16x16x32_bf16 v[98:101], v[158:161], v[196:199], v[98:101]
	v_mfma_f32_16x16x32_bf16 v[66:69], v[158:161], v[204:207], v[66:69]
	v_mfma_f32_16x16x32_bf16 v[70:73], v[150:153], v[204:207], v[70:73]
	v_mfma_f32_16x16x32_bf16 v[38:41], v[150:153], v[212:215], v[38:41]
	v_mfma_f32_16x16x32_bf16 v[34:37], v[158:161], v[212:215], v[34:37]
	v_mfma_f32_16x16x32_bf16 v[10:13], v[158:161], v[232:235], v[10:13]
	v_mfma_f32_16x16x32_bf16 v[14:17], v[150:153], v[232:235], v[14:17]
	v_mfma_f32_16x16x32_bf16 v[86:89], v[162:165], v[182:185], v[86:89]
	v_mfma_f32_16x16x32_bf16 v[82:85], v[170:173], v[182:185], v[82:85]
	v_mfma_f32_16x16x32_bf16 v[50:53], v[170:173], v[200:203], v[50:53]
	v_mfma_f32_16x16x32_bf16 v[54:57], v[162:165], v[200:203], v[54:57]
	v_mfma_f32_16x16x32_bf16 v[22:25], v[162:165], v[208:211], v[22:25]
	v_mfma_f32_16x16x32_bf16 v[18:21], v[170:173], v[208:211], v[18:21]
	v_mfma_f32_16x16x32_bf16 v[2:5], v[170:173], v[216:219], v[2:5]
	v_mfma_f32_16x16x32_bf16 v[6:9], v[162:165], v[216:219], v[6:9]
	v_mfma_f32_16x16x32_bf16 v[86:89], v[166:169], v[196:199], v[86:89]
	v_mfma_f32_16x16x32_bf16 v[82:85], v[174:177], v[196:199], v[82:85]
	v_mfma_f32_16x16x32_bf16 v[50:53], v[174:177], v[204:207], v[50:53]
	v_mfma_f32_16x16x32_bf16 v[54:57], v[166:169], v[204:207], v[54:57]
	v_mfma_f32_16x16x32_bf16 v[22:25], v[166:169], v[212:215], v[22:25]
	v_mfma_f32_16x16x32_bf16 v[18:21], v[174:177], v[212:215], v[18:21]
	v_mfma_f32_16x16x32_bf16 v[2:5], v[174:177], v[232:235], v[2:5]
	v_mfma_f32_16x16x32_bf16 v[6:9], v[166:169], v[232:235], v[6:9]
	s_setprio 0
	s_barrier
	s_add_i32 s70, 0, 0x18000
	s_add_i32 s71, 0, 0x1c000
	v_add_u32_e32 v158, s70, v180
	v_add_u32_e32 v174, s71, v180
	ds_read_b128 v[146:149], v158
	ds_read_b128 v[150:153], v158 offset:1024
	ds_read_b128 v[154:157], v158 offset:2048
	ds_read_b128 v[158:161], v158 offset:3072
	ds_read_b128 v[162:165], v174
	ds_read_b128 v[166:169], v174 offset:1024
	ds_read_b128 v[170:173], v174 offset:2048
	ds_read_b128 v[174:177], v174 offset:3072
	s_add_u32 s10, s44, 0xb0000
	s_addc_u32 s11, s45, 0
	s_mov_b32 m0, s54
	v_lshl_add_u64 v[238:239], s[10:11], 0, v[130:131]
	ds_read_b128 v[182:185], v192 offset:32768
	ds_read_b128 v[196:199], v192 offset:33792
	ds_read_b128 v[200:203], v192 offset:34816
	ds_read_b128 v[204:207], v192 offset:35840
	ds_read_b128 v[208:211], v192 offset:36864
	ds_read_b128 v[212:215], v192 offset:37888
	ds_read_b128 v[216:219], v192 offset:38912
	ds_read_b128 v[232:235], v192 offset:39936
	global_load_lds_dwordx4 v[238:239], off
	v_lshl_add_u64 v[238:239], s[10:11], 0, v[134:135]
	s_mov_b32 m0, s55
	s_nop 0
	global_load_lds_dwordx4 v[238:239], off
	s_waitcnt vmcnt(8)
	s_waitcnt lgkmcnt(0)
	s_barrier
	s_setprio 1
	v_mfma_f32_16x16x32_bf16 v[26:29], v[146:149], v[182:185], v[26:29]
	v_mfma_f32_16x16x32_bf16 v[30:33], v[154:157], v[182:185], v[30:33]
	v_mfma_f32_16x16x32_bf16 v[62:65], v[154:157], v[200:203], v[62:65]
	v_mfma_f32_16x16x32_bf16 v[58:61], v[146:149], v[200:203], v[58:61]
	v_mfma_f32_16x16x32_bf16 v[90:93], v[146:149], v[208:211], v[90:93]
	v_mfma_f32_16x16x32_bf16 v[94:97], v[154:157], v[208:211], v[94:97]
	v_mfma_f32_16x16x32_bf16 v[118:121], v[154:157], v[216:219], v[118:121]
	v_mfma_f32_16x16x32_bf16 v[114:117], v[146:149], v[216:219], v[114:117]
	v_mfma_f32_16x16x32_bf16 v[26:29], v[150:153], v[196:199], v[26:29]
	v_mfma_f32_16x16x32_bf16 v[30:33], v[158:161], v[196:199], v[30:33]
	v_mfma_f32_16x16x32_bf16 v[62:65], v[158:161], v[204:207], v[62:65]
	v_mfma_f32_16x16x32_bf16 v[58:61], v[150:153], v[204:207], v[58:61]
	v_mfma_f32_16x16x32_bf16 v[90:93], v[150:153], v[212:215], v[90:93]
	v_mfma_f32_16x16x32_bf16 v[94:97], v[158:161], v[212:215], v[94:97]
	v_mfma_f32_16x16x32_bf16 v[118:121], v[158:161], v[232:235], v[118:121]
	v_mfma_f32_16x16x32_bf16 v[114:117], v[150:153], v[232:235], v[114:117]
	v_mfma_f32_16x16x32_bf16 v[42:45], v[162:165], v[182:185], v[42:45]
	v_mfma_f32_16x16x32_bf16 v[46:49], v[170:173], v[182:185], v[46:49]
	v_mfma_f32_16x16x32_bf16 v[78:81], v[170:173], v[200:203], v[78:81]
	v_mfma_f32_16x16x32_bf16 v[74:77], v[162:165], v[200:203], v[74:77]
	v_mfma_f32_16x16x32_bf16 v[106:109], v[162:165], v[208:211], v[106:109]
	v_mfma_f32_16x16x32_bf16 v[110:113], v[170:173], v[208:211], v[110:113]
	v_mfma_f32_16x16x32_bf16 v[122:125], v[170:173], v[216:219], v[122:125]
	v_mfma_f32_16x16x32_bf16 v[126:129], v[162:165], v[216:219], v[126:129]
	v_mfma_f32_16x16x32_bf16 v[42:45], v[166:169], v[196:199], v[42:45]
	v_mfma_f32_16x16x32_bf16 v[46:49], v[174:177], v[196:199], v[46:49]
	v_mfma_f32_16x16x32_bf16 v[78:81], v[174:177], v[204:207], v[78:81]
	v_mfma_f32_16x16x32_bf16 v[74:77], v[166:169], v[204:207], v[74:77]
	v_mfma_f32_16x16x32_bf16 v[106:109], v[166:169], v[212:215], v[106:109]
	v_mfma_f32_16x16x32_bf16 v[110:113], v[174:177], v[212:215], v[110:113]
	v_mfma_f32_16x16x32_bf16 v[122:125], v[174:177], v[232:235], v[122:125]
	v_mfma_f32_16x16x32_bf16 v[126:129], v[166:169], v[232:235], v[126:129]
	s_setprio 0
	s_barrier
; #define PG8_STAGE(bufoff, gbase, voff) do { _Pragma("unroll") for (int _i = 0; _i < 2; ++_i) \
;         __builtin_amdgcn_global_load_lds((const unsigned*)((const char*)(gbase) + (voff)[_i]), (LAS unsigned*)(lds + (bufoff) + ldsw + _i * 8192), 16, 0, 0); } while (0)
; #define PG8_LDA(dst, b, h) do { _Pragma("unroll") for (int m = 0; m < 4; ++m) _Pragma("unroll") for (int k = 0; k < 2; ++k) dst[m][k] = *(const LAS bf16x8*)(lds + PG8_SA(b, h) + aoff + m * 2048 + k * 1024); } while (0)
; #define PG8_MMA(ai, bj, At, Bt) do { __builtin_amdgcn_s_setprio(1); _Pragma("unroll") for (int m = 0; m < 4; ++m) _Pragma("unroll") for (int n = 0; n < 2; ++n) _Pragma("unroll") for (int k = 0; k < 2; ++k) \
;         acc[ai][bj][m][n] = __builtin_amdgcn_mfma_f32_16x16x32_bf16(Bt[n][k], At[m][k], acc[ai][bj][m][n], 0, 0, 0); __builtin_amdgcn_s_setprio(0); } while (0)
; #define PG8_WAIT_V(n) asm volatile("s_waitcnt vmcnt(" #n ")" ::: "memory")
; #define PG8_WAIT_L(n) asm volatile("s_waitcnt lgkmcnt(" #n ")" ::: "memory")
; #define PG8_BAR __builtin_amdgcn_s_barrier()
; #define PG8_SCHED __builtin_amdgcn_sched_barrier(0)
; template <class Epi>
; __device__ __forceinline__ void gemm_phase(LAS unsigned char* lds, const Gemm g, const StaticOrder& S, const Epi& E) {
;     ...
;             PG8_LDA(At, 1, 1); PG8_STAGE(PG8_SB(1, 0), b3, voffB); PG8_STAGE(PG8_SB(1, 1), b3 + hB, voffB); PG8_STAGE(PG8_SA(1, 0), a3, voffA);
;             PG8_WAIT_V(8); PG8_WAIT_L(0); PG8_BAR; PG8_MMA(1, 0, At, B0); PG8_MMA(1, 1, At, B1); PG8_BAR; PG8_SCHED;
;         }
	s_add_i32 s10, s70, s47
	v_lshl_add_u64 v[178:179], v[178:179], 0, s[88:89]
	s_mov_b32 m0, s10
	ds_read_b128 v[182:185], v192 offset:49152
	ds_read_b128 v[196:199], v192 offset:50176
	ds_read_b128 v[200:203], v192 offset:51200
	ds_read_b128 v[204:207], v192 offset:52224
	ds_read_b128 v[208:211], v192 offset:53248
	ds_read_b128 v[212:215], v192 offset:54272
	ds_read_b128 v[216:219], v192 offset:55296
	ds_read_b128 v[232:235], v192 offset:56320
	global_load_lds_dwordx4 v[178:179], off
	s_add_i32 m0, s10, 0x2000
	s_add_u32 s10, s42, 0xb0080
	v_lshl_add_u64 v[178:179], v[186:187], 0, s[88:89]
	s_addc_u32 s11, s43, 0
	s_add_i32 s42, s71, s47
	global_load_lds_dwordx4 v[178:179], off
	v_lshl_add_u64 v[178:179], s[10:11], 0, v[132:133]
	s_mov_b32 m0, s42
	s_nop 0
	global_load_lds_dwordx4 v[178:179], off
	v_lshl_add_u64 v[178:179], s[10:11], 0, v[136:137]
	s_add_i32 m0, s42, 0x2000
	s_nop 0
	global_load_lds_dwordx4 v[178:179], off
	v_lshl_add_u64 v[178:179], v[220:221], 0, s[88:89]
	s_mov_b32 m0, s56
	s_nop 0
	global_load_lds_dwordx4 v[178:179], off
	v_lshl_add_u64 v[178:179], v[236:237], 0, s[88:89]
	s_mov_b32 m0, s57
	s_nop 0
	global_load_lds_dwordx4 v[178:179], off
	s_waitcnt vmcnt(8)
	s_waitcnt lgkmcnt(0)
	s_barrier
	s_setprio 1
	v_mfma_f32_16x16x32_bf16 v[102:105], v[146:149], v[182:185], v[102:105]
	v_mfma_f32_16x16x32_bf16 v[98:101], v[154:157], v[182:185], v[98:101]
	v_mfma_f32_16x16x32_bf16 v[66:69], v[154:157], v[200:203], v[66:69]
	v_mfma_f32_16x16x32_bf16 v[70:73], v[146:149], v[200:203], v[70:73]
	v_mfma_f32_16x16x32_bf16 v[38:41], v[146:149], v[208:211], v[38:41]
	v_mfma_f32_16x16x32_bf16 v[34:37], v[154:157], v[208:211], v[34:37]
	v_mfma_f32_16x16x32_bf16 v[10:13], v[154:157], v[216:219], v[10:13]
	v_mfma_f32_16x16x32_bf16 v[14:17], v[146:149], v[216:219], v[14:17]
	v_mfma_f32_16x16x32_bf16 v[102:105], v[150:153], v[196:199], v[102:105]
	v_mfma_f32_16x16x32_bf16 v[98:101], v[158:161], v[196:199], v[98:101]
	v_mfma_f32_16x16x32_bf16 v[66:69], v[158:161], v[204:207], v[66:69]
	v_mfma_f32_16x16x32_bf16 v[70:73], v[150:153], v[204:207], v[70:73]
	v_mfma_f32_16x16x32_bf16 v[38:41], v[150:153], v[212:215], v[38:41]
	v_mfma_f32_16x16x32_bf16 v[34:37], v[158:161], v[212:215], v[34:37]
	v_mfma_f32_16x16x32_bf16 v[10:13], v[158:161], v[232:235], v[10:13]
	v_mfma_f32_16x16x32_bf16 v[14:17], v[150:153], v[232:235], v[14:17]
	v_mfma_f32_16x16x32_bf16 v[86:89], v[162:165], v[182:185], v[86:89]
	v_mfma_f32_16x16x32_bf16 v[82:85], v[170:173], v[182:185], v[82:85]
	v_mfma_f32_16x16x32_bf16 v[50:53], v[170:173], v[200:203], v[50:53]
	v_mfma_f32_16x16x32_bf16 v[54:57], v[162:165], v[200:203], v[54:57]
	v_mfma_f32_16x16x32_bf16 v[22:25], v[162:165], v[208:211], v[22:25]
	v_mfma_f32_16x16x32_bf16 v[18:21], v[170:173], v[208:211], v[18:21]
	v_mfma_f32_16x16x32_bf16 v[2:5], v[170:173], v[216:219], v[2:5]
	v_mfma_f32_16x16x32_bf16 v[6:9], v[162:165], v[216:219], v[6:9]
	v_mfma_f32_16x16x32_bf16 v[86:89], v[166:169], v[196:199], v[86:89]
	v_mfma_f32_16x16x32_bf16 v[82:85], v[174:177], v[196:199], v[82:85]
	v_mfma_f32_16x16x32_bf16 v[50:53], v[174:177], v[204:207], v[50:53]
	v_mfma_f32_16x16x32_bf16 v[54:57], v[166:169], v[204:207], v[54:57]
	v_mfma_f32_16x16x32_bf16 v[22:25], v[166:169], v[212:215], v[22:25]
	v_mfma_f32_16x16x32_bf16 v[18:21], v[174:177], v[212:215], v[18:21]
	v_mfma_f32_16x16x32_bf16 v[2:5], v[174:177], v[232:235], v[2:5]
	v_mfma_f32_16x16x32_bf16 v[6:9], v[166:169], v[232:235], v[6:9]
	s_setprio 0
	s_barrier
	s_add_i32 s67, s67, 2
	s_add_u32 s35, s35, 0x100
	s_addc_u32 s37, s37, 0
	s_cmp_gt_u32 s67, 41
	s_mov_b64 s[10:11], s[8:9]
	s_cbranch_scc0 .LBB0_1632
	s_and_b64 vcc, exec, s[20:21]
	s_cbranch_vccz .LBB0_1635
	s_barrier
